# skinny sample-row GEMM loops: flat_load to global_load (prefetch no longer on lgkmcnt) and counted vmcnt in the three NC=2 loops; on top of e1+e4+e6
# speedup vs baseline: 1.0061x; 1.0061x over previous
; __device__ __forceinline__ int opaque_tid() { int t = threadIdx.x; asm volatile("" : "+v"(t)); return t; }
; #define SK_LOAD3() do { SK_LOAD(0, 0); if (1 < nsc) SK_LOAD(1, 1); if (2 < nsc) SK_LOAD(2, 2); } while (0)
; template <class Epi, int NC>
; __device__ __forceinline__ void skinny_phase(const bf16* __restrict__ A, int lda, int a_goff, const bf16* __restrict__ Bt, int ldb, int K, int ncg, int vcu, int G, const Epi& E, LAS float* rs_tab, LAS unsigned char* lds) {
;     const int tid = opaque_tid(), w = __builtin_amdgcn_readfirstlane(tid >> 6), lane = tid & 63, r32 = lane & 31, hi = lane >> 5, rblk = w & 1, kq = w >> 1;
;     if (Epi::NEEDS_RS) { if (tid < 256) rs_tab[tid] = row_scale_s(E.ssqS, tid); }
;     asm volatile("s_waitcnt lgkmcnt(0)" ::: "memory"); __builtin_amdgcn_s_barrier(); asm volatile("" ::: "memory");
;     constexpr int BUF = 32768 + NC * 16384, NW2 = 2 * NC;
;     const int srow = tid >> 5, sslot = tid & 31, nsc = K / 256;
;     const int st0 = srow * 512 + ((sslot ^ (srow & 15)) << 4);
;     const int rrow = 32 * rblk + r32;
;     const int NU = 4 * (ncg / NC);
;     bf16x8 ra[3][4], rw[3][NW2];
;     const bf16* pa = A; const bf16* pw[NW2];
; #pragma unroll
;     for (int i = 0; i < NW2; ++i) pw[i] = Bt;
;     ...
;     int u = vcu;
;     if (u < NU) { SK_PTRS(u); SK_LOAD3(); }
.LBB0_245:
	s_or_b64 exec, exec, s[2:3]
	s_add_u32 s2, s46, 0x24200000
	s_addc_u32 s3, s47, 0
	s_waitcnt lgkmcnt(0)
	s_barrier
	s_waitcnt vmcnt(0)
	v_and_b32_e32 v4, 31, v16
	v_ashrrev_i32_e32 v190, 5, v16
	s_cmpk_lt_i32 s65, 0x180
	s_cselect_b64 s[12:13], -1, 0
	s_cmpk_gt_i32 s65, 0x17f
	v_mov_b64_e32 v[134:135], s[0:1]
	v_mov_b64_e32 v[138:139], s[2:3]
	v_lshlrev_b32_e32 v2, 4, v4
	v_add_u32_e32 v191, 16, v190
	v_mov_b64_e32 v[140:141], s[0:1]
	v_mov_b64_e32 v[136:137], s[0:1]
	v_mov_b64_e32 v[132:133], s[0:1]
	s_cbranch_scc1 .LBB0_247
	s_lshl_b32 s5, s65, 6
	s_and_b32 s5, s5, 0xc0
	v_add_u32_e32 v6, s5, v190
	s_lshl_b32 s5, s65, 4
	s_andn2_b32 s5, s5, 63
	v_add_u32_e32 v10, s5, v190
	v_ashrrev_i32_e32 v11, 31, v10
	v_lshl_add_u64 v[8:9], s[0:1], 0, v[2:3]
	v_lshlrev_b64 v[10:11], 12, v[10:11]
	v_lshl_add_u64 v[132:133], v[8:9], 0, v[10:11]
	v_add_u32_e32 v10, s5, v191
	v_ashrrev_i32_e32 v11, 31, v10
	v_lshlrev_b64 v[10:11], 12, v[10:11]
	s_or_b32 s5, s5, 32
	v_ashrrev_i32_e32 v7, 31, v6
	v_lshl_add_u64 v[136:137], v[8:9], 0, v[10:11]
	v_add_u32_e32 v10, s5, v190
	v_lshlrev_b64 v[6:7], 12, v[6:7]
	v_ashrrev_i32_e32 v11, 31, v10
	v_lshlrev_b64 v[10:11], 12, v[10:11]
	v_lshl_add_u64 v[6:7], s[2:3], 0, v[6:7]
	v_lshl_add_u64 v[140:141], v[8:9], 0, v[10:11]
	v_add_u32_e32 v10, s5, v191
	v_lshl_add_u64 v[138:139], v[6:7], 0, v[2:3]
	v_ashrrev_i32_e32 v11, 31, v10
	v_lshlrev_b64 v[10:11], 12, v[10:11]
	v_add_co_u32_e32 v6, vcc, s71, v138
	v_lshl_add_u64 v[134:135], v[8:9], 0, v[10:11]
	s_nop 0
	v_addc_co_u32_e32 v7, vcc, 0, v139, vcc
	v_add_co_u32_e32 v8, vcc, s81, v138
	s_mov_b32 s5, 0x30000
	s_nop 0
	v_addc_co_u32_e32 v9, vcc, 0, v139, vcc
	v_add_co_u32_e32 v10, vcc, s5, v138
	s_nop 1
	v_addc_co_u32_e32 v11, vcc, 0, v139, vcc
	global_load_dwordx4 v[36:39], v[138:139], off
	global_load_dwordx4 v[40:43], v[138:139], off offset:512
	global_load_dwordx4 v[48:51], v[6:7], off
	global_load_dwordx4 v[44:47], v[6:7], off offset:512
	global_load_dwordx4 v[60:63], v[10:11], off
	global_load_dwordx4 v[56:59], v[10:11], off offset:512
	global_load_dwordx4 v[84:87], v[132:133], off
	global_load_dwordx4 v[72:75], v[132:133], off offset:512
	global_load_dwordx4 v[96:99], v[136:137], off
	global_load_dwordx4 v[92:95], v[136:137], off offset:512
	global_load_dwordx4 v[104:107], v[140:141], off
	global_load_dwordx4 v[100:103], v[140:141], off offset:512
	global_load_dwordx4 v[112:115], v[134:135], off
	global_load_dwordx4 v[108:111], v[134:135], off offset:512
	global_load_dwordx4 v[52:55], v[138:139], off offset:1024
	global_load_dwordx4 v[80:83], v[8:9], off
	global_load_dwordx4 v[64:67], v[6:7], off offset:1024
	global_load_dwordx4 v[76:79], v[8:9], off offset:512
	global_load_dwordx4 v[68:71], v[8:9], off offset:1024
	global_load_dwordx4 v[88:91], v[10:11], off offset:1024
	global_load_dwordx4 v[116:119], v[132:133], off offset:1024
	global_load_dwordx4 v[120:123], v[136:137], off offset:1024
	global_load_dwordx4 v[124:127], v[140:141], off offset:1024
	global_load_dwordx4 v[128:131], v[134:135], off offset:1024

; #define SK_WRITE(s_, b) do { LAS unsigned char* bb = lds + (b) * BUF; _Pragma("unroll") for (int i = 0; i < 4; ++i) *(LAS bf16x8*)(bb + st0 + i * 8192) = ra[s_][i]; \
;         _Pragma("unroll") for (int i = 0; i < NW2; ++i) *(LAS bf16x8*)(bb + 32768 + st0 + i * 8192) = rw[s_][i]; } while (0)
; template <class Epi, int NC>
; __device__ __forceinline__ void skinny_phase(const bf16* __restrict__ A, int lda, int a_goff, const bf16* __restrict__ Bt, int ldb, int K, int ncg, int vcu, int G, const Epi& E, LAS float* rs_tab, LAS unsigned char* lds) {
;     ...
;         f32x16 acc[NC] = {};
;         SK_WRITE(0, 0);
;         asm volatile("s_waitcnt lgkmcnt(0)" ::: "memory"); __builtin_amdgcn_s_barrier(); asm volatile("" ::: "memory");
.LBB0_250:
	v_add_u32_e32 v2, 0, v192
	s_waitcnt vmcnt(8) lgkmcnt(0)
	ds_write_b128 v2, v[36:39]
	ds_write_b128 v2, v[48:51] offset:8192
	ds_write_b128 v2, v[80:83] offset:16384
	ds_write_b128 v2, v[60:63] offset:24576
	ds_write_b128 v2, v[84:87] offset:32768
	ds_write_b128 v2, v[96:99] offset:40960
	ds_write_b128 v2, v[104:107] offset:49152
	ds_write_b128 v2, v[112:115] offset:57344
	s_waitcnt lgkmcnt(0)
	s_barrier
	v_mov_b32_e32 v4, 0
	s_mov_b32 s4, s65
	s_mov_b64 s[2:3], 0
	s_mov_b32 s5, 0
	s_mov_b32 s6, 0
	v_mov_b32_e32 v5, v4
	v_mov_b32_e32 v6, v4
	v_mov_b32_e32 v7, v4
	v_mov_b32_e32 v8, v4
	v_mov_b32_e32 v9, v4
	v_mov_b32_e32 v10, v4
	v_mov_b32_e32 v11, v4
	v_mov_b32_e32 v12, v4
	v_mov_b32_e32 v13, v4
	v_mov_b32_e32 v14, v4
	v_mov_b32_e32 v15, v4
	v_mov_b32_e32 v16, v4
	v_mov_b32_e32 v17, v4
	v_mov_b32_e32 v18, v4
	v_mov_b32_e32 v19, v4
	v_mov_b32_e32 v20, v4
	v_mov_b32_e32 v21, v4
	v_mov_b32_e32 v22, v4
	v_mov_b32_e32 v23, v4
	v_mov_b32_e32 v24, v4
	v_mov_b32_e32 v25, v4
	v_mov_b32_e32 v26, v4
	v_mov_b32_e32 v27, v4
	v_mov_b32_e32 v28, v4
	v_mov_b32_e32 v29, v4
	v_mov_b32_e32 v30, v4
	v_mov_b32_e32 v31, v4
	v_mov_b32_e32 v32, v4
	v_mov_b32_e32 v33, v4
	v_mov_b32_e32 v34, v4
	v_mov_b32_e32 v35, v4
	s_branch .LBB0_253

.LBB0_253:
	s_and_b32 s8, s5, 0x10000
	s_xor_b32 s7, s8, 0x10000
	s_add_i32 s7, s7, 0
	s_cmp_lt_u32 s6, 6
	s_cbranch_scc1 .Lsk250_a
	s_waitcnt vmcnt(0)
.Lsk250_a:
	s_waitcnt vmcnt(6)
	s_cmp_gt_u32 s6, 4
	s_cselect_b64 s[12:13], -1, 0
	v_add_u32_e32 v2, s7, v192
	s_and_b64 vcc, exec, s[12:13]
	ds_write_b128 v2, v[40:43]
	ds_write_b128 v2, v[44:47] offset:8192
	ds_write_b128 v2, v[76:79] offset:16384
	ds_write_b128 v2, v[56:59] offset:24576
	ds_write_b128 v2, v[72:75] offset:32768
	ds_write_b128 v2, v[92:95] offset:40960
	ds_write_b128 v2, v[100:103] offset:49152
	ds_write_b128 v2, v[108:111] offset:57344
	s_cbranch_vccnz .LBB0_255
	v_lshl_add_u64 v[60:61], v[138:139], 0, s[2:3]
	v_add_co_u32_e32 v48, vcc, 0x10000, v60
	v_lshl_add_u64 v[84:85], v[132:133], 0, s[2:3]
	s_nop 0
	v_addc_co_u32_e32 v49, vcc, 0, v61, vcc
	v_add_co_u32_e32 v62, vcc, 0x20000, v60
	global_load_dwordx4 v[36:39], v[60:61], off offset:1536
	s_nop 0
	global_load_dwordx4 v[48:51], v[48:49], off offset:1536
	v_addc_co_u32_e32 v63, vcc, 0, v61, vcc
	v_add_co_u32_e32 v60, vcc, 0x30000, v60
	v_lshl_add_u64 v[96:97], v[136:137], 0, s[2:3]
	s_nop 0
	v_addc_co_u32_e32 v61, vcc, 0, v61, vcc
	v_lshl_add_u64 v[104:105], v[140:141], 0, s[2:3]
	v_lshl_add_u64 v[112:113], v[134:135], 0, s[2:3]
	global_load_dwordx4 v[80:83], v[62:63], off offset:1536
	s_nop 0
	global_load_dwordx4 v[60:63], v[60:61], off offset:1536
	s_nop 0
	global_load_dwordx4 v[84:87], v[84:85], off offset:1536
	s_nop 0
	global_load_dwordx4 v[96:99], v[96:97], off offset:1536
	s_nop 0
	global_load_dwordx4 v[104:107], v[104:105], off offset:1536
	s_nop 0
	global_load_dwordx4 v[112:115], v[112:113], off offset:1536
.LBB0_255:
	s_add_i32 s8, s8, 0
	v_add_u32_e32 v156, s8, v194
	v_add_u32_e32 v157, s8, v195
	v_add_u32_e32 v147, v156, v207
	v_add_u32_e32 v146, v157, v207
	ds_read_b128 v[148:151], v147
	ds_read_b128 v[152:155], v146 offset:32768
	s_cmp_lt_u32 s6, 6
	s_cselect_b64 s[18:19], -1, 0
	s_cmp_gt_u32 s6, 5
	s_waitcnt lgkmcnt(0)
	v_mfma_f32_32x32x16_bf16 v[4:19], v[152:155], v[148:151], v[4:19]
	ds_read_b128 v[152:155], v146 offset:49152
	s_waitcnt lgkmcnt(0)
	v_mfma_f32_32x32x16_bf16 v[20:35], v[152:155], v[148:151], v[20:35]
	v_add_u32_e32 v148, v156, v208
	v_add_u32_e32 v149, v157, v208
	ds_read_b128 v[150:153], v148
	ds_read_b128 v[172:175], v149 offset:32768
	s_waitcnt lgkmcnt(0)
	v_mfma_f32_32x32x16_bf16 v[4:19], v[172:175], v[150:153], v[4:19]
	ds_read_b128 v[172:175], v149 offset:49152
	s_waitcnt lgkmcnt(0)
	v_mfma_f32_32x32x16_bf16 v[20:35], v[172:175], v[150:153], v[20:35]
	v_add_u32_e32 v151, v156, v209
	v_add_u32_e32 v150, v157, v209
	ds_read_b128 v[152:155], v151
	ds_read_b128 v[172:175], v150 offset:32768
	s_waitcnt lgkmcnt(0)
	v_mfma_f32_32x32x16_bf16 v[4:19], v[172:175], v[152:155], v[4:19]
	ds_read_b128 v[172:175], v150 offset:49152
	s_waitcnt lgkmcnt(0)
	v_mfma_f32_32x32x16_bf16 v[20:35], v[172:175], v[152:155], v[20:35]
	v_add_u32_e32 v153, v156, v210
	v_add_u32_e32 v152, v157, v210
	ds_read_b128 v[172:175], v153
	ds_read_b128 v[176:179], v152 offset:32768
	s_waitcnt lgkmcnt(0)
	v_mfma_f32_32x32x16_bf16 v[4:19], v[176:179], v[172:175], v[4:19]
	ds_read_b128 v[176:179], v152 offset:49152
	s_waitcnt lgkmcnt(0)
	s_barrier
	s_waitcnt lgkmcnt(0)
	v_mfma_f32_32x32x16_bf16 v[20:35], v[176:179], v[172:175], v[20:35]
	s_cbranch_scc1 .LBB0_257
	v_add_u32_e32 v154, s8, v192
	s_waitcnt vmcnt(8)
	ds_write_b128 v154, v[52:55]
	ds_write_b128 v154, v[64:67] offset:8192
	ds_write_b128 v154, v[68:71] offset:16384
	ds_write_b128 v154, v[88:91] offset:24576
	ds_write_b128 v154, v[116:119] offset:32768
	ds_write_b128 v154, v[120:123] offset:40960
	ds_write_b128 v154, v[124:127] offset:49152
	ds_write_b128 v154, v[128:131] offset:57344
.LBB0_257:
	s_cmp_gt_u32 s6, 3
	s_cbranch_scc1 .LBB0_259
	v_lshl_add_u64 v[56:57], v[138:139], 0, s[2:3]
	v_add_co_u32_e32 v44, vcc, 0x10000, v56
	v_lshl_add_u64 v[72:73], v[132:133], 0, s[2:3]
	s_nop 0
	v_addc_co_u32_e32 v45, vcc, 0, v57, vcc
	v_add_co_u32_e32 v58, vcc, 0x20000, v56
	global_load_dwordx4 v[40:43], v[56:57], off offset:2048
	s_nop 0
	global_load_dwordx4 v[44:47], v[44:45], off offset:2048
	v_addc_co_u32_e32 v59, vcc, 0, v57, vcc
	v_add_co_u32_e32 v56, vcc, 0x30000, v56
	v_lshl_add_u64 v[92:93], v[136:137], 0, s[2:3]
	s_nop 0
	v_addc_co_u32_e32 v57, vcc, 0, v57, vcc
	v_lshl_add_u64 v[100:101], v[140:141], 0, s[2:3]
	v_lshl_add_u64 v[108:109], v[134:135], 0, s[2:3]
	global_load_dwordx4 v[76:79], v[58:59], off offset:2048
	s_nop 0
	global_load_dwordx4 v[56:59], v[56:57], off offset:2048
	s_nop 0
	global_load_dwordx4 v[72:75], v[72:73], off offset:2048
	s_nop 0
	global_load_dwordx4 v[92:95], v[92:93], off offset:2048
	s_nop 0
	global_load_dwordx4 v[100:103], v[100:101], off offset:2048
	s_nop 0
	global_load_dwordx4 v[108:111], v[108:109], off offset:2048
; #define SK_LOAD3() do { SK_LOAD(0, 0); if (1 < nsc) SK_LOAD(1, 1); if (2 < nsc) SK_LOAD(2, 2); } while (0)
; template <class Epi, int NC>
; __device__ __forceinline__ void skinny_phase(const bf16* __restrict__ A, int lda, int a_goff, const bf16* __restrict__ Bt, int ldb, int K, int ncg, int vcu, int G, const Epi& E, LAS float* rs_tab, LAS unsigned char* lds) {
;     ...
;         const int un = u + G;
;         if (un < NU) { SK_PTRS(un); SK_LOAD3(); }
.LBB0_259:
	v_add_u32_e32 v154, s7, v194
	v_add_u32_e32 v155, s7, v195
	v_add_u32_e32 v156, v154, v207
	ds_read_b128 v[172:175], v156
	v_add_u32_e32 v156, v155, v207
	ds_read_b128 v[176:179], v156 offset:32768
	s_andn2_b64 vcc, exec, s[18:19]
	s_waitcnt lgkmcnt(0)
	v_mfma_f32_32x32x16_bf16 v[4:19], v[176:179], v[172:175], v[4:19]
	ds_read_b128 v[176:179], v156 offset:49152
	v_add_u32_e32 v156, v154, v208
	s_waitcnt lgkmcnt(0)
	v_mfma_f32_32x32x16_bf16 v[20:35], v[176:179], v[172:175], v[20:35]
	ds_read_b128 v[172:175], v156
	v_add_u32_e32 v156, v155, v208
	ds_read_b128 v[176:179], v156 offset:32768
	s_waitcnt lgkmcnt(0)
	v_mfma_f32_32x32x16_bf16 v[4:19], v[176:179], v[172:175], v[4:19]
	ds_read_b128 v[176:179], v156 offset:49152
	v_add_u32_e32 v156, v154, v209
	v_add_u32_e32 v154, v154, v210
	s_waitcnt lgkmcnt(0)
	v_mfma_f32_32x32x16_bf16 v[20:35], v[176:179], v[172:175], v[20:35]
	ds_read_b128 v[172:175], v156
	v_add_u32_e32 v156, v155, v209
	ds_read_b128 v[176:179], v156 offset:32768
	s_waitcnt lgkmcnt(0)
	v_mfma_f32_32x32x16_bf16 v[4:19], v[176:179], v[172:175], v[4:19]
	ds_read_b128 v[176:179], v156 offset:49152
	s_waitcnt lgkmcnt(0)
	v_mfma_f32_32x32x16_bf16 v[20:35], v[176:179], v[172:175], v[20:35]
	ds_read_b128 v[172:175], v154
	v_add_u32_e32 v154, v155, v210
	ds_read_b128 v[176:179], v154 offset:32768
	s_waitcnt lgkmcnt(0)
	v_mfma_f32_32x32x16_bf16 v[4:19], v[176:179], v[172:175], v[4:19]
	ds_read_b128 v[176:179], v154 offset:49152
	s_waitcnt lgkmcnt(0)
	s_barrier
	s_waitcnt lgkmcnt(0)
	v_mfma_f32_32x32x16_bf16 v[20:35], v[176:179], v[172:175], v[20:35]
	s_cbranch_vccnz .LBB0_252
	s_cmpk_eq_i32 s2, 0xa00
	s_cbranch_scc1 .LBB0_262
	s_waitcnt vmcnt(8)
	ds_write_b128 v2, v[36:39]
	ds_write_b128 v2, v[48:51] offset:8192
	ds_write_b128 v2, v[80:83] offset:16384
	ds_write_b128 v2, v[60:63] offset:24576
	ds_write_b128 v2, v[84:87] offset:32768
	ds_write_b128 v2, v[96:99] offset:40960
	ds_write_b128 v2, v[104:107] offset:49152
	ds_write_b128 v2, v[112:115] offset:57344
.LBB0_262:
	s_cmp_gt_u32 s6, 2
	s_cbranch_scc1 .LBB0_251
	v_lshl_add_u64 v[68:69], v[138:139], 0, s[2:3]
	v_add_co_u32_e32 v64, vcc, 0x10000, v68
	v_lshl_add_u64 v[116:117], v[132:133], 0, s[2:3]
	s_nop 0
	v_addc_co_u32_e32 v65, vcc, 0, v69, vcc
	v_add_co_u32_e32 v70, vcc, 0x20000, v68
	v_lshl_add_u64 v[120:121], v[136:137], 0, s[2:3]
	s_nop 0
	v_addc_co_u32_e32 v71, vcc, 0, v69, vcc
	v_add_co_u32_e32 v88, vcc, 0x30000, v68
	v_lshl_add_u64 v[124:125], v[140:141], 0, s[2:3]
	s_nop 0
	v_addc_co_u32_e32 v89, vcc, 0, v69, vcc
	v_lshl_add_u64 v[128:129], v[134:135], 0, s[2:3]
	global_load_dwordx4 v[52:55], v[68:69], off offset:2560
	s_nop 0
	global_load_dwordx4 v[64:67], v[64:65], off offset:2560
	s_nop 0
	global_load_dwordx4 v[68:71], v[70:71], off offset:2560
	s_nop 0
	global_load_dwordx4 v[88:91], v[88:89], off offset:2560
	s_nop 0
	global_load_dwordx4 v[116:119], v[116:117], off offset:2560
	s_nop 0
	global_load_dwordx4 v[120:123], v[120:121], off offset:2560
	s_nop 0
	global_load_dwordx4 v[124:127], v[124:125], off offset:2560
	s_nop 0
	global_load_dwordx4 v[128:131], v[128:129], off offset:2560
	s_branch .LBB0_251
.LBB0_264:
	s_add_i32 s65, s4, s62
	s_cmpk_gt_i32 s65, 0x17f
	s_cselect_b64 s[2:3], -1, 0
	s_cmpk_lt_i32 s65, 0x180
	s_cbranch_scc0 .LBB0_266
	s_lshl_b32 s5, s65, 6
	s_and_b32 s5, s5, 0xc0
	s_waitcnt vmcnt(0)
	v_add_u32_e32 v36, s5, v190
	s_lshl_b32 s5, s65, 4
	s_andn2_b32 s5, s5, 63
	v_add_u32_e32 v38, s5, v190
	v_ashrrev_i32_e32 v39, 31, v38
	v_lshlrev_b64 v[38:39], 12, v[38:39]
	v_lshl_add_u64 v[132:133], v[144:145], 0, v[38:39]
	v_add_u32_e32 v38, s5, v191
	v_ashrrev_i32_e32 v37, 31, v36
	v_ashrrev_i32_e32 v39, 31, v38
	v_lshlrev_b64 v[36:37], 12, v[36:37]
	v_lshlrev_b64 v[38:39], 12, v[38:39]
	s_or_b32 s5, s5, 32
	v_lshl_add_u64 v[136:137], v[144:145], 0, v[38:39]
	v_add_u32_e32 v38, s5, v190
	v_lshl_add_u64 v[138:139], v[142:143], 0, v[36:37]
	v_ashrrev_i32_e32 v39, 31, v38
	v_lshlrev_b64 v[38:39], 12, v[38:39]
	v_add_co_u32_e32 v64, vcc, s71, v138
	v_lshl_add_u64 v[140:141], v[144:145], 0, v[38:39]
	s_nop 0
	v_addc_co_u32_e32 v65, vcc, 0, v139, vcc
	v_add_u32_e32 v38, s5, v191
	v_add_co_u32_e32 v68, vcc, s81, v138
	v_ashrrev_i32_e32 v39, 31, v38
	s_nop 0
	v_addc_co_u32_e32 v69, vcc, 0, v139, vcc
	s_mov_b32 s5, 0x30000
	v_lshlrev_b64 v[38:39], 12, v[38:39]
	v_add_co_u32_e32 v88, vcc, s5, v138
	v_lshl_add_u64 v[134:135], v[144:145], 0, v[38:39]
	s_nop 0
	v_addc_co_u32_e32 v89, vcc, 0, v139, vcc
	global_load_dwordx4 v[36:39], v[138:139], off
	global_load_dwordx4 v[40:43], v[138:139], off offset:512
	global_load_dwordx4 v[48:51], v[64:65], off
	global_load_dwordx4 v[44:47], v[64:65], off offset:512
	global_load_dwordx4 v[60:63], v[88:89], off
	global_load_dwordx4 v[56:59], v[88:89], off offset:512
	global_load_dwordx4 v[84:87], v[132:133], off
	global_load_dwordx4 v[72:75], v[132:133], off offset:512
	global_load_dwordx4 v[96:99], v[136:137], off
	global_load_dwordx4 v[92:95], v[136:137], off offset:512
	global_load_dwordx4 v[104:107], v[140:141], off
	global_load_dwordx4 v[100:103], v[140:141], off offset:512
	global_load_dwordx4 v[112:115], v[134:135], off
	global_load_dwordx4 v[108:111], v[134:135], off offset:512
	global_load_dwordx4 v[52:55], v[138:139], off offset:1024
	global_load_dwordx4 v[80:83], v[68:69], off
	s_nop 0
	global_load_dwordx4 v[64:67], v[64:65], off offset:1024
	s_nop 0
	global_load_dwordx4 v[76:79], v[68:69], off offset:512
	s_nop 0
	global_load_dwordx4 v[68:71], v[68:69], off offset:1024
	s_nop 0
	global_load_dwordx4 v[88:91], v[88:89], off offset:1024
	s_nop 0
	global_load_dwordx4 v[116:119], v[132:133], off offset:1024
	global_load_dwordx4 v[120:123], v[136:137], off offset:1024
	global_load_dwordx4 v[124:127], v[140:141], off offset:1024
	global_load_dwordx4 v[128:131], v[134:135], off offset:1024

; __device__ __forceinline__ int opaque_tid() { int t = threadIdx.x; asm volatile("" : "+v"(t)); return t; }
; #define SK_LOAD3() do { SK_LOAD(0, 0); if (1 < nsc) SK_LOAD(1, 1); if (2 < nsc) SK_LOAD(2, 2); } while (0)
; template <class Epi, int NC>
; __device__ __forceinline__ void skinny_phase(const bf16* __restrict__ A, int lda, int a_goff, const bf16* __restrict__ Bt, int ldb, int K, int ncg, int vcu, int G, const Epi& E, LAS float* rs_tab, LAS unsigned char* lds) {
;     const int tid = opaque_tid(), w = __builtin_amdgcn_readfirstlane(tid >> 6), lane = tid & 63, r32 = lane & 31, hi = lane >> 5, rblk = w & 1, kq = w >> 1;
;     if (Epi::NEEDS_RS) { if (tid < 256) rs_tab[tid] = row_scale_s(E.ssqS, tid); }
;     asm volatile("s_waitcnt lgkmcnt(0)" ::: "memory"); __builtin_amdgcn_s_barrier(); asm volatile("" ::: "memory");
;     constexpr int BUF = 32768 + NC * 16384, NW2 = 2 * NC;
;     const int srow = tid >> 5, sslot = tid & 31, nsc = K / 256;
;     const int st0 = srow * 512 + ((sslot ^ (srow & 15)) << 4);
;     const int rrow = 32 * rblk + r32;
;     const int NU = 4 * (ncg / NC);
;     bf16x8 ra[3][4], rw[3][NW2];
;     const bf16* pa = A; const bf16* pw[NW2];
; #pragma unroll
;     for (int i = 0; i < NW2; ++i) pw[i] = Bt;
;     ...
;     int u = vcu;
;     if (u < NU) { SK_PTRS(u); SK_LOAD3(); }
.LBB0_623:
	s_waitcnt vmcnt(0)
	v_mov_b32_e32 v4, v0
	s_waitcnt lgkmcnt(0)
	s_barrier
	v_readfirstlane_b32 s4, v4
	s_cmpk_gt_i32 s65, 0xff
	s_cbranch_scc1 .LBB0_647
	s_add_u32 s18, s2, 0x30600000
	s_addc_u32 s19, s3, 0
	s_ashr_i32 s5, s4, 6
	s_waitcnt lgkmcnt(0)
	v_and_b32_e32 v5, 31, v4
	s_lshl_b32 s6, s5, 5
	v_and_or_b32 v106, s6, 32, v5
	s_lshl_b64 s[6:7], s[10:11], 16
	s_add_u32 s2, s2, s6
	s_addc_u32 s3, s3, s7
	s_add_u32 s2, s2, 0x41e00000
	v_ashrrev_i32_e32 v104, 5, v4
	s_addc_u32 s3, s3, 0
	s_lshl_b32 s6, s65, 6
	v_bitop3_b32 v2, v104, v5, 15 bitop3:0x6c
	v_lshlrev_b32_e32 v6, 9, v104
	s_and_b32 s6, s6, 0xc0
	v_lshl_or_b32 v105, v2, 4, v6
	v_add_u32_e32 v6, s6, v104
	s_lshl_b32 s6, s65, 3
	v_ashrrev_i32_e32 v7, 31, v6
	s_andn2_b32 s6, s6, 31
	v_add_u32_e32 v10, s6, v104
	v_lshlrev_b64 v[6:7], 12, v[6:7]
	v_lshlrev_b32_e32 v2, 4, v5
	v_ashrrev_i32_e32 v11, 31, v10
	v_lshl_add_u64 v[6:7], s[18:19], 0, v[6:7]
	v_lshlrev_b64 v[12:13], 12, v[10:11]
	v_add_u32_e32 v10, 16, v10
	v_lshl_add_u64 v[98:99], v[6:7], 0, v[2:3]
	v_ashrrev_i32_e32 v11, 31, v10
	v_lshl_add_u64 v[92:93], s[12:13], 0, v[2:3]
	v_add_co_u32_e32 v6, vcc, s71, v98
	v_lshlrev_b64 v[10:11], 12, v[10:11]
	s_nop 0
	v_addc_co_u32_e32 v7, vcc, 0, v99, vcc
	v_lshl_add_u64 v[96:97], v[92:93], 0, v[10:11]
	v_add_co_u32_e32 v10, vcc, s81, v98
	s_mov_b32 s6, 0x30000
	s_nop 0
	v_addc_co_u32_e32 v11, vcc, 0, v99, vcc
	v_lshl_add_u64 v[94:95], v[92:93], 0, v[12:13]
	v_add_co_u32_e32 v12, vcc, s6, v98
	global_load_dwordx4 v[20:23], v[98:99], off
	s_nop 0
	v_addc_co_u32_e32 v13, vcc, 0, v99, vcc
	global_load_dwordx4 v[24:27], v[6:7], off
	global_load_dwordx4 v[32:35], v[10:11], off
	global_load_dwordx4 v[36:39], v[12:13], off
	global_load_dwordx4 v[44:47], v[94:95], off
	global_load_dwordx4 v[48:51], v[96:97], off
	global_load_dwordx4 v[28:31], v[98:99], off offset:512
	global_load_dwordx4 v[40:43], v[6:7], off offset:512
	global_load_dwordx4 v[56:59], v[10:11], off offset:512
	global_load_dwordx4 v[60:63], v[12:13], off offset:512
	global_load_dwordx4 v[68:71], v[94:95], off offset:512
	global_load_dwordx4 v[72:75], v[96:97], off offset:512
	global_load_dwordx4 v[52:55], v[98:99], off offset:1024
	global_load_dwordx4 v[64:67], v[6:7], off offset:1024
	global_load_dwordx4 v[76:79], v[10:11], off offset:1024
	global_load_dwordx4 v[80:83], v[12:13], off offset:1024
	global_load_dwordx4 v[84:87], v[94:95], off offset:1024
	global_load_dwordx4 v[88:91], v[96:97], off offset:1024
	s_ashr_i32 s6, s4, 4
	v_and_b32_e32 v9, 63, v4
	v_bfe_u32 v14, v4, 5, 1
	s_and_b32 s6, s6, -8
	v_and_b32_e32 v4, 15, v4
	v_lshlrev_b32_e32 v8, 3, v5
	v_or_b32_e32 v2, s6, v14
	v_lshlrev_b32_e32 v109, 9, v5
	s_lshl_b32 s5, s5, 12
	v_bitop3_b32 v5, s6, v4, v14 bitop3:0x36
	s_add_i32 s5, s5, 0
	v_lshlrev_b32_e32 v112, 4, v5
	v_bitop3_b32 v5, v2, v4, 2 bitop3:0x36
	s_cmpk_lt_u32 s4, 0x80
	v_lshlrev_b32_e32 v113, 4, v5
	v_bitop3_b32 v5, v2, v4, 4 bitop3:0x36
	v_bitop3_b32 v2, v2, v4, 6 bitop3:0x36
	v_add_u32_e32 v107, 0, v105
	v_lshlrev_b32_e32 v108, 9, v106
	v_lshl_add_u32 v110, v9, 2, s5
	s_cselect_b64 s[12:13], -1, 0
	v_lshlrev_b32_e32 v111, 2, v14
	v_cmp_gt_u32_e64 s[38:39], 32, v9
	v_lshlrev_b32_e32 v114, 4, v5
	v_lshlrev_b32_e32 v115, 4, v2
	v_lshlrev_b32_e32 v100, 1, v8
	s_branch .LBB0_627

.LBB0_628:
	s_and_b32 s7, 1, s5
	s_cselect_b32 s6, 0, 0xc000
	s_add_i32 s6, s6, 0
	s_cmp_lt_u32 s5, 5
	s_cselect_b64 s[40:41], -1, 0
	s_cmp_gt_u32 s5, 4
	s_cselect_b64 s[36:37], -1, 0
	v_add_u32_e32 v2, s6, v105
	s_and_b64 vcc, exec, s[36:37]
	s_waitcnt vmcnt(0)
	ds_write_b128 v2, v[28:31]
	ds_write_b128 v2, v[40:43] offset:8192
	ds_write_b128 v2, v[56:59] offset:16384
	ds_write_b128 v2, v[60:63] offset:24576
	ds_write_b128 v2, v[68:71] offset:32768
	ds_write_b128 v2, v[72:75] offset:40960
	s_cbranch_vccnz .LBB0_630
	v_lshl_add_u64 v[32:33], v[98:99], 0, s[20:21]
	v_add_co_u32_e32 v24, vcc, 0x10000, v32
	v_lshl_add_u64 v[44:45], v[94:95], 0, s[20:21]
	s_nop 0
	v_addc_co_u32_e32 v25, vcc, 0, v33, vcc
	v_add_co_u32_e32 v34, vcc, 0x20000, v32
	v_lshl_add_u64 v[48:49], v[96:97], 0, s[20:21]
	s_nop 0
	v_addc_co_u32_e32 v35, vcc, 0, v33, vcc
	v_add_co_u32_e32 v36, vcc, 0x30000, v32
	global_load_dwordx4 v[20:23], v[32:33], off offset:1536
	s_nop 0
	global_load_dwordx4 v[24:27], v[24:25], off offset:1536
	v_addc_co_u32_e32 v37, vcc, 0, v33, vcc
	global_load_dwordx4 v[32:35], v[34:35], off offset:1536
	s_nop 0
	global_load_dwordx4 v[36:39], v[36:37], off offset:1536
	s_nop 0
	global_load_dwordx4 v[44:47], v[44:45], off offset:1536
	s_nop 0
	global_load_dwordx4 v[48:51], v[48:49], off offset:1536

.LBB0_632:
	s_cmp_gt_u32 s5, 3
	s_cbranch_scc1 .LBB0_634
	v_lshl_add_u64 v[56:57], v[98:99], 0, s[20:21]
	v_add_co_u32_e32 v40, vcc, 0x10000, v56
	v_lshl_add_u64 v[68:69], v[94:95], 0, s[20:21]
	s_nop 0
	v_addc_co_u32_e32 v41, vcc, 0, v57, vcc
	v_add_co_u32_e32 v58, vcc, 0x20000, v56
	v_lshl_add_u64 v[72:73], v[96:97], 0, s[20:21]
	s_nop 0
	v_addc_co_u32_e32 v59, vcc, 0, v57, vcc
	v_add_co_u32_e32 v60, vcc, 0x30000, v56
	global_load_dwordx4 v[28:31], v[56:57], off offset:2048
	s_nop 0
	global_load_dwordx4 v[40:43], v[40:41], off offset:2048
	v_addc_co_u32_e32 v61, vcc, 0, v57, vcc
	global_load_dwordx4 v[56:59], v[58:59], off offset:2048
	s_nop 0
	global_load_dwordx4 v[60:63], v[60:61], off offset:2048
	s_nop 0
	global_load_dwordx4 v[68:71], v[68:69], off offset:2048
	s_nop 0
	global_load_dwordx4 v[72:75], v[72:73], off offset:2048

.LBB0_637:
	s_cmp_gt_u32 s5, 2
	s_cbranch_scc1 .LBB0_639
	v_lshl_add_u64 v[76:77], v[98:99], 0, s[20:21]
	v_add_co_u32_e32 v64, vcc, 0x10000, v76
	v_lshl_add_u64 v[84:85], v[94:95], 0, s[20:21]
	s_nop 0
	v_addc_co_u32_e32 v65, vcc, 0, v77, vcc
	v_add_co_u32_e32 v78, vcc, 0x20000, v76
	v_lshl_add_u64 v[88:89], v[96:97], 0, s[20:21]
	s_nop 0
	v_addc_co_u32_e32 v79, vcc, 0, v77, vcc
	v_add_co_u32_e32 v80, vcc, 0x30000, v76
	global_load_dwordx4 v[52:55], v[76:77], off offset:2560
	s_nop 0
	global_load_dwordx4 v[64:67], v[64:65], off offset:2560
	v_addc_co_u32_e32 v81, vcc, 0, v77, vcc
	global_load_dwordx4 v[76:79], v[78:79], off offset:2560
	s_nop 0
	global_load_dwordx4 v[80:83], v[80:81], off offset:2560
	s_nop 0
	global_load_dwordx4 v[84:87], v[84:85], off offset:2560
	s_nop 0
	global_load_dwordx4 v[88:91], v[88:89], off offset:2560

; #define SK_LOAD3() do { SK_LOAD(0, 0); if (1 < nsc) SK_LOAD(1, 1); if (2 < nsc) SK_LOAD(2, 2); } while (0)
; template <class Epi, int NC>
; __device__ __forceinline__ void skinny_phase(const bf16* __restrict__ A, int lda, int a_goff, const bf16* __restrict__ Bt, int ldb, int K, int ncg, int vcu, int G, const Epi& E, LAS float* rs_tab, LAS unsigned char* lds) {
;     ...
;         const int un = u + G;
;         if (un < NU) { SK_PTRS(un); SK_LOAD3(); }
.LBB0_642:
	s_add_i32 s65, s4, s64
	s_cmpk_gt_i32 s65, 0xff
	s_cselect_b64 s[20:21], -1, 0
	s_cmpk_lt_i32 s65, 0x100
	s_cbranch_scc0 .LBB0_644
	s_lshl_b32 s5, s65, 6
	s_and_b32 s5, s5, 0xc0
	s_waitcnt vmcnt(0)
	v_add_u32_e32 v20, s5, v104
	v_ashrrev_i32_e32 v21, 31, v20
	v_lshlrev_b64 v[20:21], 12, v[20:21]
	v_lshl_add_u64 v[20:21], s[18:19], 0, v[20:21]
	s_lshl_b32 s5, s65, 3
	v_mov_b32_e32 v101, v3
	s_andn2_b32 s5, s5, 31
	v_lshl_add_u64 v[98:99], v[20:21], 0, v[100:101]
	v_add_u32_e32 v22, s5, v104
	v_ashrrev_i32_e32 v23, 31, v22
	v_add_co_u32_e32 v56, vcc, s71, v98
	v_lshlrev_b64 v[24:25], 12, v[22:23]
	s_nop 0
	v_addc_co_u32_e32 v57, vcc, 0, v99, vcc
	v_add_u32_e32 v22, 16, v22
	v_add_co_u32_e32 v76, vcc, s81, v98
	v_ashrrev_i32_e32 v23, 31, v22
	s_nop 0
	v_addc_co_u32_e32 v77, vcc, 0, v99, vcc
	s_mov_b32 s5, 0x30000
	v_lshlrev_b64 v[22:23], 12, v[22:23]
	v_add_co_u32_e32 v80, vcc, s5, v98
	v_lshl_add_u64 v[94:95], v[92:93], 0, v[24:25]
	v_lshl_add_u64 v[96:97], v[92:93], 0, v[22:23]
	v_addc_co_u32_e32 v81, vcc, 0, v99, vcc
	global_load_dwordx4 v[20:23], v[98:99], off
	global_load_dwordx4 v[28:31], v[98:99], off offset:512
	global_load_dwordx4 v[24:27], v[56:57], off
	global_load_dwordx4 v[40:43], v[56:57], off offset:512
	global_load_dwordx4 v[36:39], v[80:81], off
	global_load_dwordx4 v[60:63], v[80:81], off offset:512
	global_load_dwordx4 v[44:47], v[94:95], off
	global_load_dwordx4 v[68:71], v[94:95], off offset:512
	global_load_dwordx4 v[48:51], v[96:97], off
	global_load_dwordx4 v[72:75], v[96:97], off offset:512
	global_load_dwordx4 v[52:55], v[98:99], off offset:1024
	global_load_dwordx4 v[32:35], v[76:77], off
	global_load_dwordx4 v[64:67], v[56:57], off offset:1024
	s_nop 0
	global_load_dwordx4 v[56:59], v[76:77], off offset:512
	s_nop 0
	global_load_dwordx4 v[76:79], v[76:77], off offset:1024
	s_nop 0
	global_load_dwordx4 v[80:83], v[80:81], off offset:1024
	s_nop 0
	global_load_dwordx4 v[84:87], v[94:95], off offset:1024
	global_load_dwordx4 v[88:91], v[96:97], off offset:1024

; __device__ __forceinline__ int opaque_tid() { int t = threadIdx.x; asm volatile("" : "+v"(t)); return t; }
; #define SK_LOAD3() do { SK_LOAD(0, 0); if (1 < nsc) SK_LOAD(1, 1); if (2 < nsc) SK_LOAD(2, 2); } while (0)
; template <class Epi, int NC>
; __device__ __forceinline__ void skinny_phase(const bf16* __restrict__ A, int lda, int a_goff, const bf16* __restrict__ Bt, int ldb, int K, int ncg, int vcu, int G, const Epi& E, LAS float* rs_tab, LAS unsigned char* lds) {
;     const int tid = opaque_tid(), w = __builtin_amdgcn_readfirstlane(tid >> 6), lane = tid & 63, r32 = lane & 31, hi = lane >> 5, rblk = w & 1, kq = w >> 1;
;     if (Epi::NEEDS_RS) { if (tid < 256) rs_tab[tid] = row_scale_s(E.ssqS, tid); }
;     asm volatile("s_waitcnt lgkmcnt(0)" ::: "memory"); __builtin_amdgcn_s_barrier(); asm volatile("" ::: "memory");
;     constexpr int BUF = 32768 + NC * 16384, NW2 = 2 * NC;
;     const int srow = tid >> 5, sslot = tid & 31, nsc = K / 256;
;     const int st0 = srow * 512 + ((sslot ^ (srow & 15)) << 4);
;     const int rrow = 32 * rblk + r32;
;     const int NU = 4 * (ncg / NC);
;     bf16x8 ra[3][4], rw[3][NW2];
;     const bf16* pa = A; const bf16* pw[NW2];
; #pragma unroll
;     for (int i = 0; i < NW2; ++i) pw[i] = Bt;
;     ...
;     int u = vcu;
;     if (u < NU) { SK_PTRS(u); SK_LOAD3(); }
.LBB0_2009:
	s_or_b64 exec, exec, s[2:3]
	s_add_u32 s2, s48, 0x24200000
	s_addc_u32 s3, s49, 0
	s_waitcnt lgkmcnt(0)
	s_barrier
	v_and_b32_e32 v4, 31, v16
	v_ashrrev_i32_e32 v192, 5, v16
	s_cmpk_lt_i32 s67, 0x200
	s_cselect_b64 s[12:13], -1, 0
	s_cmpk_gt_i32 s67, 0x1ff
	v_mov_b64_e32 v[134:135], s[46:47]
	v_mov_b64_e32 v[138:139], s[2:3]
	v_lshlrev_b32_e32 v2, 4, v4
	v_add_u32_e32 v193, 16, v192
	v_mov_b64_e32 v[140:141], s[46:47]
	v_mov_b64_e32 v[136:137], s[46:47]
	v_mov_b64_e32 v[132:133], s[46:47]
	s_cbranch_scc1 .LBB0_2011
	s_lshl_b32 s5, s67, 6
	s_and_b32 s5, s5, 0xc0
	v_add_u32_e32 v6, s5, v192
	s_lshl_b32 s5, s67, 4
	s_andn2_b32 s5, s5, 63
	v_add_u32_e32 v10, s5, v192
	v_ashrrev_i32_e32 v11, 31, v10
	v_lshl_add_u64 v[8:9], s[46:47], 0, v[2:3]
	v_lshlrev_b64 v[10:11], 12, v[10:11]
	v_lshl_add_u64 v[132:133], v[8:9], 0, v[10:11]
	v_add_u32_e32 v10, s5, v193
	v_ashrrev_i32_e32 v11, 31, v10
	v_lshlrev_b64 v[10:11], 12, v[10:11]
	s_or_b32 s5, s5, 32
	v_ashrrev_i32_e32 v7, 31, v6
	v_lshl_add_u64 v[136:137], v[8:9], 0, v[10:11]
	v_add_u32_e32 v10, s5, v192
	v_lshlrev_b64 v[6:7], 12, v[6:7]
	v_ashrrev_i32_e32 v11, 31, v10
	v_lshlrev_b64 v[10:11], 12, v[10:11]
	v_lshl_add_u64 v[6:7], s[2:3], 0, v[6:7]
	v_lshl_add_u64 v[140:141], v[8:9], 0, v[10:11]
	v_add_u32_e32 v10, s5, v193
	v_lshl_add_u64 v[138:139], v[6:7], 0, v[2:3]
	v_ashrrev_i32_e32 v11, 31, v10
	v_lshlrev_b64 v[10:11], 12, v[10:11]
	v_add_co_u32_e32 v6, vcc, s71, v138
	v_lshl_add_u64 v[134:135], v[8:9], 0, v[10:11]
	s_nop 0
	v_addc_co_u32_e32 v7, vcc, 0, v139, vcc
	v_add_co_u32_e32 v8, vcc, s81, v138
	s_mov_b32 s5, 0x30000
	s_nop 0
	v_addc_co_u32_e32 v9, vcc, 0, v139, vcc
	v_add_co_u32_e32 v10, vcc, s5, v138
	s_nop 1
	v_addc_co_u32_e32 v11, vcc, 0, v139, vcc
	global_load_dwordx4 v[36:39], v[138:139], off
	global_load_dwordx4 v[40:43], v[138:139], off offset:512
	global_load_dwordx4 v[48:51], v[6:7], off
	global_load_dwordx4 v[44:47], v[6:7], off offset:512
	global_load_dwordx4 v[60:63], v[10:11], off
	global_load_dwordx4 v[56:59], v[10:11], off offset:512
	global_load_dwordx4 v[84:87], v[132:133], off
	global_load_dwordx4 v[72:75], v[132:133], off offset:512
	global_load_dwordx4 v[96:99], v[136:137], off
	global_load_dwordx4 v[92:95], v[136:137], off offset:512
	global_load_dwordx4 v[104:107], v[140:141], off
	global_load_dwordx4 v[100:103], v[140:141], off offset:512
	global_load_dwordx4 v[112:115], v[134:135], off
	global_load_dwordx4 v[108:111], v[134:135], off offset:512
	global_load_dwordx4 v[52:55], v[138:139], off offset:1024
	global_load_dwordx4 v[80:83], v[8:9], off
	global_load_dwordx4 v[64:67], v[6:7], off offset:1024
	global_load_dwordx4 v[76:79], v[8:9], off offset:512
	global_load_dwordx4 v[68:71], v[8:9], off offset:1024
	global_load_dwordx4 v[88:91], v[10:11], off offset:1024
	global_load_dwordx4 v[116:119], v[132:133], off offset:1024
	global_load_dwordx4 v[120:123], v[136:137], off offset:1024
	global_load_dwordx4 v[124:127], v[140:141], off offset:1024
	global_load_dwordx4 v[128:131], v[134:135], off offset:1024

; #define SK_WRITE(s_, b) do { LAS unsigned char* bb = lds + (b) * BUF; _Pragma("unroll") for (int i = 0; i < 4; ++i) *(LAS bf16x8*)(bb + st0 + i * 8192) = ra[s_][i]; \
;         _Pragma("unroll") for (int i = 0; i < NW2; ++i) *(LAS bf16x8*)(bb + 32768 + st0 + i * 8192) = rw[s_][i]; } while (0)
; template <class Epi, int NC>
; __device__ __forceinline__ void skinny_phase(const bf16* __restrict__ A, int lda, int a_goff, const bf16* __restrict__ Bt, int ldb, int K, int ncg, int vcu, int G, const Epi& E, LAS float* rs_tab, LAS unsigned char* lds) {
;     ...
;         f32x16 acc[NC] = {};
;         SK_WRITE(0, 0);
;         asm volatile("s_waitcnt lgkmcnt(0)" ::: "memory"); __builtin_amdgcn_s_barrier(); asm volatile("" ::: "memory");
.LBB0_2015:
	v_add_u32_e32 v2, 0, v194
	s_waitcnt vmcnt(8) lgkmcnt(0)
	ds_write_b128 v2, v[36:39]
	ds_write_b128 v2, v[48:51] offset:8192
	ds_write_b128 v2, v[80:83] offset:16384
	ds_write_b128 v2, v[60:63] offset:24576
	ds_write_b128 v2, v[84:87] offset:32768
	ds_write_b128 v2, v[96:99] offset:40960
	ds_write_b128 v2, v[104:107] offset:49152
	ds_write_b128 v2, v[112:115] offset:57344
	s_waitcnt lgkmcnt(0)
	s_barrier
	v_mov_b32_e32 v4, 0
	s_mov_b32 s4, s67
	s_mov_b64 s[2:3], 0
	s_mov_b32 s5, 0
	s_mov_b32 s6, 0
	v_mov_b32_e32 v5, v4
	v_mov_b32_e32 v6, v4
	v_mov_b32_e32 v7, v4
	v_mov_b32_e32 v8, v4
	v_mov_b32_e32 v9, v4
	v_mov_b32_e32 v10, v4
	v_mov_b32_e32 v11, v4
	v_mov_b32_e32 v12, v4
	v_mov_b32_e32 v13, v4
	v_mov_b32_e32 v14, v4
	v_mov_b32_e32 v15, v4
	v_mov_b32_e32 v16, v4
	v_mov_b32_e32 v17, v4
	v_mov_b32_e32 v18, v4
	v_mov_b32_e32 v19, v4
	v_mov_b32_e32 v20, v4
	v_mov_b32_e32 v21, v4
	v_mov_b32_e32 v22, v4
	v_mov_b32_e32 v23, v4
	v_mov_b32_e32 v24, v4
	v_mov_b32_e32 v25, v4
	v_mov_b32_e32 v26, v4
	v_mov_b32_e32 v27, v4
	v_mov_b32_e32 v28, v4
	v_mov_b32_e32 v29, v4
	v_mov_b32_e32 v30, v4
	v_mov_b32_e32 v31, v4
	v_mov_b32_e32 v32, v4
	v_mov_b32_e32 v33, v4
	v_mov_b32_e32 v34, v4
	v_mov_b32_e32 v35, v4
	s_branch .LBB0_2018

.Lsk2015_a:
	s_waitcnt vmcnt(6)
	s_cmp_gt_u32 s6, 4
	s_cselect_b64 s[18:19], -1, 0
	v_add_u32_e32 v2, s7, v194
	s_and_b64 vcc, exec, s[18:19]
	ds_write_b128 v2, v[40:43]
	ds_write_b128 v2, v[44:47] offset:8192
	ds_write_b128 v2, v[76:79] offset:16384
	ds_write_b128 v2, v[56:59] offset:24576
	ds_write_b128 v2, v[72:75] offset:32768
	ds_write_b128 v2, v[92:95] offset:40960
	ds_write_b128 v2, v[100:103] offset:49152
	ds_write_b128 v2, v[108:111] offset:57344
	s_cbranch_vccnz .LBB0_2020
	v_lshl_add_u64 v[60:61], v[138:139], 0, s[2:3]
	v_add_co_u32_e32 v48, vcc, 0x10000, v60
	v_lshl_add_u64 v[84:85], v[132:133], 0, s[2:3]
	s_nop 0
	v_addc_co_u32_e32 v49, vcc, 0, v61, vcc
	v_add_co_u32_e32 v62, vcc, 0x20000, v60
	global_load_dwordx4 v[36:39], v[60:61], off offset:1536
	s_nop 0
	global_load_dwordx4 v[48:51], v[48:49], off offset:1536
	v_addc_co_u32_e32 v63, vcc, 0, v61, vcc
	v_add_co_u32_e32 v60, vcc, 0x30000, v60
	v_lshl_add_u64 v[96:97], v[136:137], 0, s[2:3]
	s_nop 0
	v_addc_co_u32_e32 v61, vcc, 0, v61, vcc
	v_lshl_add_u64 v[104:105], v[140:141], 0, s[2:3]
	v_lshl_add_u64 v[112:113], v[134:135], 0, s[2:3]
	global_load_dwordx4 v[80:83], v[62:63], off offset:1536
	s_nop 0
	global_load_dwordx4 v[60:63], v[60:61], off offset:1536
	s_nop 0
	global_load_dwordx4 v[84:87], v[84:85], off offset:1536
	s_nop 0
	global_load_dwordx4 v[96:99], v[96:97], off offset:1536
	s_nop 0
	global_load_dwordx4 v[104:107], v[104:105], off offset:1536
	s_nop 0
	global_load_dwordx4 v[112:115], v[112:113], off offset:1536
.LBB0_2020:
	s_add_i32 s8, s8, 0
	v_add_u32_e32 v156, s8, v196
	v_add_u32_e32 v157, s8, v197
	v_add_u32_e32 v147, v156, v209
	v_add_u32_e32 v146, v157, v209
	ds_read_b128 v[148:151], v147
	ds_read_b128 v[152:155], v146 offset:32768
	s_cmp_lt_u32 s6, 6
	s_cselect_b64 s[20:21], -1, 0
	s_cmp_gt_u32 s6, 5
	s_waitcnt lgkmcnt(0)
	v_mfma_f32_32x32x16_bf16 v[4:19], v[152:155], v[148:151], v[4:19]
	ds_read_b128 v[152:155], v146 offset:49152
	s_waitcnt lgkmcnt(0)
	v_mfma_f32_32x32x16_bf16 v[20:35], v[152:155], v[148:151], v[20:35]
	v_add_u32_e32 v148, v156, v210
	v_add_u32_e32 v149, v157, v210
	ds_read_b128 v[150:153], v148
	ds_read_b128 v[172:175], v149 offset:32768
	s_waitcnt lgkmcnt(0)
	v_mfma_f32_32x32x16_bf16 v[4:19], v[172:175], v[150:153], v[4:19]
	ds_read_b128 v[172:175], v149 offset:49152
	s_waitcnt lgkmcnt(0)
	v_mfma_f32_32x32x16_bf16 v[20:35], v[172:175], v[150:153], v[20:35]
	v_add_u32_e32 v151, v156, v211
	v_add_u32_e32 v150, v157, v211
	ds_read_b128 v[152:155], v151
	ds_read_b128 v[172:175], v150 offset:32768
	s_waitcnt lgkmcnt(0)
	v_mfma_f32_32x32x16_bf16 v[4:19], v[172:175], v[152:155], v[4:19]
	ds_read_b128 v[172:175], v150 offset:49152
	s_waitcnt lgkmcnt(0)
	v_mfma_f32_32x32x16_bf16 v[20:35], v[172:175], v[152:155], v[20:35]
	v_add_u32_e32 v153, v156, v212
	v_add_u32_e32 v152, v157, v212
	ds_read_b128 v[172:175], v153
	ds_read_b128 v[176:179], v152 offset:32768
	s_waitcnt lgkmcnt(0)
	v_mfma_f32_32x32x16_bf16 v[4:19], v[176:179], v[172:175], v[4:19]
	ds_read_b128 v[176:179], v152 offset:49152
	s_waitcnt lgkmcnt(0)
	s_barrier
	s_waitcnt lgkmcnt(0)
	v_mfma_f32_32x32x16_bf16 v[20:35], v[176:179], v[172:175], v[20:35]
	s_cbranch_scc1 .LBB0_2022
	v_add_u32_e32 v154, s8, v194
	s_waitcnt vmcnt(8)
	ds_write_b128 v154, v[52:55]
	ds_write_b128 v154, v[64:67] offset:8192
	ds_write_b128 v154, v[68:71] offset:16384
	ds_write_b128 v154, v[88:91] offset:24576
	ds_write_b128 v154, v[116:119] offset:32768
	ds_write_b128 v154, v[120:123] offset:40960
	ds_write_b128 v154, v[124:127] offset:49152
	ds_write_b128 v154, v[128:131] offset:57344

.LBB0_2024:
	v_add_u32_e32 v154, s7, v196
	v_add_u32_e32 v155, s7, v197
	v_add_u32_e32 v156, v154, v209
	ds_read_b128 v[172:175], v156
	v_add_u32_e32 v156, v155, v209
	ds_read_b128 v[176:179], v156 offset:32768
	s_andn2_b64 vcc, exec, s[20:21]
	s_waitcnt lgkmcnt(0)
	v_mfma_f32_32x32x16_bf16 v[4:19], v[176:179], v[172:175], v[4:19]
	ds_read_b128 v[176:179], v156 offset:49152
	v_add_u32_e32 v156, v154, v210
	s_waitcnt lgkmcnt(0)
	v_mfma_f32_32x32x16_bf16 v[20:35], v[176:179], v[172:175], v[20:35]
	ds_read_b128 v[172:175], v156
	v_add_u32_e32 v156, v155, v210
	ds_read_b128 v[176:179], v156 offset:32768
	s_waitcnt lgkmcnt(0)
	v_mfma_f32_32x32x16_bf16 v[4:19], v[176:179], v[172:175], v[4:19]
	ds_read_b128 v[176:179], v156 offset:49152
	v_add_u32_e32 v156, v154, v211
	v_add_u32_e32 v154, v154, v212
	s_waitcnt lgkmcnt(0)
	v_mfma_f32_32x32x16_bf16 v[20:35], v[176:179], v[172:175], v[20:35]
	ds_read_b128 v[172:175], v156
	v_add_u32_e32 v156, v155, v211
	ds_read_b128 v[176:179], v156 offset:32768
	s_waitcnt lgkmcnt(0)
	v_mfma_f32_32x32x16_bf16 v[4:19], v[176:179], v[172:175], v[4:19]
	ds_read_b128 v[176:179], v156 offset:49152
	s_waitcnt lgkmcnt(0)
	v_mfma_f32_32x32x16_bf16 v[20:35], v[176:179], v[172:175], v[20:35]
	ds_read_b128 v[172:175], v154
	v_add_u32_e32 v154, v155, v212
	ds_read_b128 v[176:179], v154 offset:32768
	s_waitcnt lgkmcnt(0)
	v_mfma_f32_32x32x16_bf16 v[4:19], v[176:179], v[172:175], v[4:19]
	ds_read_b128 v[176:179], v154 offset:49152
	s_waitcnt lgkmcnt(0)
	s_barrier
	s_waitcnt lgkmcnt(0)
	v_mfma_f32_32x32x16_bf16 v[20:35], v[176:179], v[172:175], v[20:35]
	s_cbranch_vccnz .LBB0_2017
	s_cmpk_eq_i32 s2, 0xa00
	s_cbranch_scc1 .LBB0_2027
	s_waitcnt vmcnt(8)
	ds_write_b128 v2, v[36:39]
	ds_write_b128 v2, v[48:51] offset:8192
	ds_write_b128 v2, v[80:83] offset:16384
	ds_write_b128 v2, v[60:63] offset:24576
	ds_write_b128 v2, v[84:87] offset:32768
	ds_write_b128 v2, v[96:99] offset:40960
	ds_write_b128 v2, v[104:107] offset:49152
	ds_write_b128 v2, v[112:115] offset:57344

; #define SK_LOAD3() do { SK_LOAD(0, 0); if (1 < nsc) SK_LOAD(1, 1); if (2 < nsc) SK_LOAD(2, 2); } while (0)
; template <class Epi, int NC>
; __device__ __forceinline__ void skinny_phase(const bf16* __restrict__ A, int lda, int a_goff, const bf16* __restrict__ Bt, int ldb, int K, int ncg, int vcu, int G, const Epi& E, LAS float* rs_tab, LAS unsigned char* lds) {
;     ...
;         const int un = u + G;
;         if (un < NU) { SK_PTRS(un); SK_LOAD3(); }
.LBB0_2029:
	s_add_i32 s67, s4, s64
	s_cmpk_gt_i32 s67, 0x1ff
	s_cselect_b64 s[18:19], -1, 0
	s_cmpk_lt_i32 s67, 0x200
	s_cbranch_scc0 .LBB0_2031
	s_lshl_b32 s2, s67, 6
	s_and_b32 s2, s2, 0xc0
	s_waitcnt vmcnt(0)
	v_add_u32_e32 v36, s2, v192
	s_lshl_b32 s2, s67, 4
	s_andn2_b32 s2, s2, 63
	v_add_u32_e32 v38, s2, v192
	v_ashrrev_i32_e32 v39, 31, v38
	v_lshlrev_b64 v[38:39], 12, v[38:39]
	v_lshl_add_u64 v[132:133], v[144:145], 0, v[38:39]
	v_add_u32_e32 v38, s2, v193
	v_ashrrev_i32_e32 v37, 31, v36
	v_ashrrev_i32_e32 v39, 31, v38
	v_lshlrev_b64 v[36:37], 12, v[36:37]
	v_lshlrev_b64 v[38:39], 12, v[38:39]
	s_or_b32 s2, s2, 32
	v_lshl_add_u64 v[136:137], v[144:145], 0, v[38:39]
	v_add_u32_e32 v38, s2, v192
	v_lshl_add_u64 v[138:139], v[142:143], 0, v[36:37]
	v_ashrrev_i32_e32 v39, 31, v38
	v_lshlrev_b64 v[38:39], 12, v[38:39]
	v_add_co_u32_e32 v64, vcc, s71, v138
	v_lshl_add_u64 v[140:141], v[144:145], 0, v[38:39]
	s_nop 0
	v_addc_co_u32_e32 v65, vcc, 0, v139, vcc
	v_add_u32_e32 v38, s2, v193
	v_add_co_u32_e32 v68, vcc, s81, v138
	v_ashrrev_i32_e32 v39, 31, v38
	s_nop 0
	v_addc_co_u32_e32 v69, vcc, 0, v139, vcc
	s_mov_b32 s2, 0x30000
	v_lshlrev_b64 v[38:39], 12, v[38:39]
	v_add_co_u32_e32 v88, vcc, s2, v138
	v_lshl_add_u64 v[134:135], v[144:145], 0, v[38:39]
	s_nop 0
	v_addc_co_u32_e32 v89, vcc, 0, v139, vcc
	global_load_dwordx4 v[36:39], v[138:139], off
	global_load_dwordx4 v[40:43], v[138:139], off offset:512
	global_load_dwordx4 v[48:51], v[64:65], off
	global_load_dwordx4 v[44:47], v[64:65], off offset:512
	global_load_dwordx4 v[60:63], v[88:89], off
	global_load_dwordx4 v[56:59], v[88:89], off offset:512
	global_load_dwordx4 v[84:87], v[132:133], off
	global_load_dwordx4 v[72:75], v[132:133], off offset:512
	global_load_dwordx4 v[96:99], v[136:137], off
	global_load_dwordx4 v[92:95], v[136:137], off offset:512
	global_load_dwordx4 v[104:107], v[140:141], off
	global_load_dwordx4 v[100:103], v[140:141], off offset:512
	global_load_dwordx4 v[112:115], v[134:135], off
	global_load_dwordx4 v[108:111], v[134:135], off offset:512
	global_load_dwordx4 v[52:55], v[138:139], off offset:1024
	global_load_dwordx4 v[80:83], v[68:69], off
	s_nop 0
	global_load_dwordx4 v[64:67], v[64:65], off offset:1024
	s_nop 0
	global_load_dwordx4 v[76:79], v[68:69], off offset:512
	s_nop 0
	global_load_dwordx4 v[68:71], v[68:69], off offset:1024
	s_nop 0
	global_load_dwordx4 v[88:91], v[88:89], off offset:1024
	s_nop 0
	global_load_dwordx4 v[116:119], v[132:133], off offset:1024
	global_load_dwordx4 v[120:123], v[136:137], off offset:1024
	global_load_dwordx4 v[124:127], v[140:141], off offset:1024
	global_load_dwordx4 v[128:131], v[134:135], off offset:1024

; __device__ __forceinline__ int opaque_tid() { int t = threadIdx.x; asm volatile("" : "+v"(t)); return t; }
; #define SK_LOAD3() do { SK_LOAD(0, 0); if (1 < nsc) SK_LOAD(1, 1); if (2 < nsc) SK_LOAD(2, 2); } while (0)
; template <class Epi, int NC>
; __device__ __forceinline__ void skinny_phase(const bf16* __restrict__ A, int lda, int a_goff, const bf16* __restrict__ Bt, int ldb, int K, int ncg, int vcu, int G, const Epi& E, LAS float* rs_tab, LAS unsigned char* lds) {
;     const int tid = opaque_tid(), w = __builtin_amdgcn_readfirstlane(tid >> 6), lane = tid & 63, r32 = lane & 31, hi = lane >> 5, rblk = w & 1, kq = w >> 1;
;     if (Epi::NEEDS_RS) { if (tid < 256) rs_tab[tid] = row_scale_s(E.ssqS, tid); }
;     asm volatile("s_waitcnt lgkmcnt(0)" ::: "memory"); __builtin_amdgcn_s_barrier(); asm volatile("" ::: "memory");
;     constexpr int BUF = 32768 + NC * 16384, NW2 = 2 * NC;
;     const int srow = tid >> 5, sslot = tid & 31, nsc = K / 256;
;     const int st0 = srow * 512 + ((sslot ^ (srow & 15)) << 4);
;     const int rrow = 32 * rblk + r32;
;     const int NU = 4 * (ncg / NC);
;     bf16x8 ra[3][4], rw[3][NW2];
;     const bf16* pa = A; const bf16* pw[NW2];
; #pragma unroll
;     for (int i = 0; i < NW2; ++i) pw[i] = Bt;
;     ...
;     int u = vcu;
;     if (u < NU) { SK_PTRS(u); SK_LOAD3(); }
.LBB0_2574:
	s_waitcnt vmcnt(0)
	v_mov_b32_e32 v4, v0
	s_waitcnt lgkmcnt(0)
	s_barrier
	v_readfirstlane_b32 s4, v4
	s_cmpk_gt_i32 s65, 0xff
	s_cbranch_scc1 .LBB0_2598
	s_add_u32 s18, s2, 0x3c900000
	s_addc_u32 s19, s3, 0
	s_ashr_i32 s5, s4, 6
	s_waitcnt lgkmcnt(0)
	v_and_b32_e32 v5, 31, v4
	s_lshl_b32 s6, s5, 5
	v_and_or_b32 v106, s6, 32, v5
	s_lshl_b64 s[6:7], s[10:11], 16
	s_add_u32 s2, s2, s6
	s_addc_u32 s3, s3, s7
	s_add_u32 s2, s2, 0x41e00000
	v_ashrrev_i32_e32 v104, 5, v4
	s_addc_u32 s3, s3, 0
	s_lshl_b32 s6, s65, 6
	v_bitop3_b32 v2, v104, v5, 15 bitop3:0x6c
	v_lshlrev_b32_e32 v6, 9, v104
	s_and_b32 s6, s6, 0xc0
	v_lshl_or_b32 v105, v2, 4, v6
	v_add_u32_e32 v6, s6, v104
	s_lshl_b32 s6, s65, 3
	v_ashrrev_i32_e32 v7, 31, v6
	s_andn2_b32 s6, s6, 31
	v_add_u32_e32 v10, s6, v104
	v_lshlrev_b64 v[6:7], 12, v[6:7]
	v_lshlrev_b32_e32 v2, 4, v5
	v_ashrrev_i32_e32 v11, 31, v10
	v_lshl_add_u64 v[6:7], s[18:19], 0, v[6:7]
	v_lshlrev_b64 v[12:13], 12, v[10:11]
	v_add_u32_e32 v10, 16, v10
	v_lshl_add_u64 v[98:99], v[6:7], 0, v[2:3]
	v_ashrrev_i32_e32 v11, 31, v10
	v_lshl_add_u64 v[92:93], s[12:13], 0, v[2:3]
	v_add_co_u32_e32 v6, vcc, s71, v98
	v_lshlrev_b64 v[10:11], 12, v[10:11]
	s_nop 0
	v_addc_co_u32_e32 v7, vcc, 0, v99, vcc
	v_lshl_add_u64 v[96:97], v[92:93], 0, v[10:11]
	v_add_co_u32_e32 v10, vcc, s81, v98
	s_mov_b32 s6, 0x30000
	s_nop 0
	v_addc_co_u32_e32 v11, vcc, 0, v99, vcc
	v_lshl_add_u64 v[94:95], v[92:93], 0, v[12:13]
	v_add_co_u32_e32 v12, vcc, s6, v98
	global_load_dwordx4 v[20:23], v[98:99], off
	s_nop 0
	v_addc_co_u32_e32 v13, vcc, 0, v99, vcc
	global_load_dwordx4 v[24:27], v[6:7], off
	global_load_dwordx4 v[32:35], v[10:11], off
	global_load_dwordx4 v[36:39], v[12:13], off
	global_load_dwordx4 v[44:47], v[94:95], off
	global_load_dwordx4 v[48:51], v[96:97], off
	global_load_dwordx4 v[28:31], v[98:99], off offset:512
	global_load_dwordx4 v[40:43], v[6:7], off offset:512
	global_load_dwordx4 v[56:59], v[10:11], off offset:512
	global_load_dwordx4 v[60:63], v[12:13], off offset:512
	global_load_dwordx4 v[68:71], v[94:95], off offset:512
	global_load_dwordx4 v[72:75], v[96:97], off offset:512
	global_load_dwordx4 v[52:55], v[98:99], off offset:1024
	global_load_dwordx4 v[64:67], v[6:7], off offset:1024
	global_load_dwordx4 v[76:79], v[10:11], off offset:1024
	global_load_dwordx4 v[80:83], v[12:13], off offset:1024
	global_load_dwordx4 v[84:87], v[94:95], off offset:1024
	global_load_dwordx4 v[88:91], v[96:97], off offset:1024
	s_ashr_i32 s6, s4, 4
	v_and_b32_e32 v9, 63, v4
	v_bfe_u32 v14, v4, 5, 1
	s_and_b32 s6, s6, -8
	v_and_b32_e32 v4, 15, v4
	v_lshlrev_b32_e32 v8, 3, v5
	v_or_b32_e32 v2, s6, v14
	v_lshlrev_b32_e32 v109, 9, v5
	s_lshl_b32 s5, s5, 12
	v_bitop3_b32 v5, s6, v4, v14 bitop3:0x36
	s_add_i32 s5, s5, 0
	v_lshlrev_b32_e32 v112, 4, v5
	v_bitop3_b32 v5, v2, v4, 2 bitop3:0x36
	s_cmpk_lt_u32 s4, 0x80
	v_lshlrev_b32_e32 v113, 4, v5
	v_bitop3_b32 v5, v2, v4, 4 bitop3:0x36
	v_bitop3_b32 v2, v2, v4, 6 bitop3:0x36
	v_add_u32_e32 v107, 0, v105
	v_lshlrev_b32_e32 v108, 9, v106
	v_lshl_add_u32 v110, v9, 2, s5
	s_cselect_b64 s[12:13], -1, 0
	v_lshlrev_b32_e32 v111, 2, v14
	v_cmp_gt_u32_e64 s[38:39], 32, v9
	v_lshlrev_b32_e32 v114, 4, v5
	v_lshlrev_b32_e32 v115, 4, v2
	v_lshlrev_b32_e32 v100, 1, v8
	s_brev_b32 s8, 32
	s_branch .LBB0_2578

; __device__ __forceinline__ int opaque_tid() { int t = threadIdx.x; asm volatile("" : "+v"(t)); return t; }
; template <class Epi, int NC>
; __device__ __forceinline__ void skinny_phase(const bf16* __restrict__ A, int lda, int a_goff, const bf16* __restrict__ Bt, int ldb, int K, int ncg, int vcu, int G, const Epi& E, LAS float* rs_tab, LAS unsigned char* lds) {
;     const int tid = opaque_tid(), w = __builtin_amdgcn_readfirstlane(tid >> 6), lane = tid & 63, r32 = lane & 31, hi = lane >> 5, rblk = w & 1, kq = w >> 1;
;     if (Epi::NEEDS_RS) { if (tid < 256) rs_tab[tid] = row_scale_s(E.ssqS, tid); }
;     asm volatile("s_waitcnt lgkmcnt(0)" ::: "memory"); __builtin_amdgcn_s_barrier(); asm volatile("" ::: "memory");
;     constexpr int BUF = 32768 + NC * 16384, NW2 = 2 * NC;
;     const int srow = tid >> 5, sslot = tid & 31, nsc = K / 256;
;     const int st0 = srow * 512 + ((sslot ^ (srow & 15)) << 4);
;     const int rrow = 32 * rblk + r32;
;     const int NU = 4 * (ncg / NC);
;     bf16x8 ra[3][4], rw[3][NW2];
;     const bf16* pa = A; const bf16* pw[NW2];
; #pragma unroll
;     for (int i = 0; i < NW2; ++i) pw[i] = Bt;
.LBB0_2671:
	s_or_b64 exec, exec, s[2:3]
	s_waitcnt lgkmcnt(0)
	s_barrier
	s_cmpk_gt_i32 s62, 0x2bf
	s_cbranch_scc1 .LBB0_2692
	s_ashr_i32 s5, s4, 6
	v_and_b32_e32 v10, 31, v16
	s_lshl_b32 s2, s5, 5
	v_and_or_b32 v185, s2, 32, v10
	s_add_u32 s2, s18, 0x24200000
	v_ashrrev_i32_e32 v182, 5, v16
	s_addc_u32 s3, s19, 0
	s_lshl_b32 s7, s62, 6
	v_bitop3_b32 v2, v182, v10, 15 bitop3:0x6c
	v_lshlrev_b32_e32 v4, 9, v182
	s_ashr_i32 s6, s62, 1
	s_and_b32 s7, s7, 0xc0
	v_lshl_or_b32 v184, v2, 4, v4
	v_add_u32_e32 v4, s7, v182
	s_lshl_b32 s7, s6, 5
	s_lshl_b32 s6, s6, 4
	s_and_b32 s7, s7, 0xffffff00
	s_and_b32 s6, s6, 0x60
	v_and_b32_e32 v183, 15, v182
	s_or_b32 s6, s7, s6
	v_lshlrev_b32_e32 v6, 3, v182
	v_or_b32_e32 v8, s6, v183
	v_and_b32_e32 v186, 0xffffff80, v6
	v_add_u32_e32 v6, v8, v186
	v_lshlrev_b32_e32 v2, 4, v10
	v_ashrrev_i32_e32 v7, 31, v6
	v_lshl_add_u64 v[132:133], s[12:13], 0, v[2:3]
	v_lshlrev_b64 v[6:7], 12, v[6:7]
	v_add_u32_e32 v187, 0x80, v186
	v_lshl_add_u64 v[134:135], v[132:133], 0, v[6:7]
	v_add_u32_e32 v6, v8, v187
	v_ashrrev_i32_e32 v7, 31, v6
	v_lshlrev_b64 v[6:7], 12, v[6:7]
	v_or_b32_e32 v8, 16, v8
	v_ashrrev_i32_e32 v5, 31, v4
	v_lshl_add_u64 v[136:137], v[132:133], 0, v[6:7]
	v_add_u32_e32 v6, v8, v186
	v_lshlrev_b64 v[4:5], 12, v[4:5]
	v_ashrrev_i32_e32 v7, 31, v6
	v_lshlrev_b64 v[6:7], 12, v[6:7]
	v_lshl_add_u64 v[4:5], s[2:3], 0, v[4:5]
	v_lshl_add_u64 v[138:139], v[132:133], 0, v[6:7]
	v_add_u32_e32 v6, v8, v187
	v_lshl_add_u64 v[142:143], v[4:5], 0, v[2:3]
	v_ashrrev_i32_e32 v7, 31, v6
	v_lshlrev_b64 v[6:7], 12, v[6:7]
	v_add_co_u32_e32 v4, vcc, s71, v142
	v_lshl_add_u64 v[140:141], v[132:133], 0, v[6:7]
	s_nop 0
	v_addc_co_u32_e32 v5, vcc, 0, v143, vcc
	v_add_co_u32_e32 v6, vcc, s81, v142
	s_mov_b32 s6, 0x30000
	s_nop 0
	v_addc_co_u32_e32 v7, vcc, 0, v143, vcc
	v_add_co_u32_e32 v8, vcc, s6, v142
	s_nop 1
	v_addc_co_u32_e32 v9, vcc, 0, v143, vcc
	global_load_dwordx4 v[36:39], v[142:143], off
	global_load_dwordx4 v[40:43], v[4:5], off
	global_load_dwordx4 v[48:51], v[6:7], off
	global_load_dwordx4 v[44:47], v[8:9], off
	global_load_dwordx4 v[56:59], v[134:135], off
	global_load_dwordx4 v[60:63], v[136:137], off
	global_load_dwordx4 v[68:71], v[138:139], off
	global_load_dwordx4 v[72:75], v[140:141], off
	global_load_dwordx4 v[52:55], v[142:143], off offset:512
	global_load_dwordx4 v[64:67], v[4:5], off offset:512
	global_load_dwordx4 v[80:83], v[6:7], off offset:512
	global_load_dwordx4 v[76:79], v[8:9], off offset:512
	global_load_dwordx4 v[88:91], v[134:135], off offset:512
	global_load_dwordx4 v[92:95], v[136:137], off offset:512
	global_load_dwordx4 v[100:103], v[138:139], off offset:512
	global_load_dwordx4 v[104:107], v[140:141], off offset:512
	global_load_dwordx4 v[84:87], v[142:143], off offset:1024
	global_load_dwordx4 v[96:99], v[4:5], off offset:1024
	global_load_dwordx4 v[108:111], v[6:7], off offset:1024
	global_load_dwordx4 v[112:115], v[8:9], off offset:1024
	global_load_dwordx4 v[116:119], v[134:135], off offset:1024
	global_load_dwordx4 v[120:123], v[136:137], off offset:1024
	global_load_dwordx4 v[124:127], v[138:139], off offset:1024
	global_load_dwordx4 v[128:131], v[140:141], off offset:1024
	s_ashr_i32 s6, s4, 4
	v_bfe_u32 v12, v16, 5, 1
	s_and_b32 s6, s6, -8
	v_and_b32_e32 v5, 15, v16
	v_or_b32_e32 v4, s6, v12
	v_lshl_add_u64 v[144:145], s[2:3], 0, v[2:3]
	s_lshl_b32 s2, s5, 13
	v_bitop3_b32 v6, s6, v5, v12 bitop3:0x36
	s_add_i32 s2, s2, 0
	v_lshlrev_b32_e32 v191, 4, v6
	v_bitop3_b32 v6, v4, v5, 2 bitop3:0x36
	v_and_b32_e32 v11, 63, v16
	s_cmpk_lt_u32 s4, 0x80
	v_lshlrev_b32_e32 v2, 2, v12
	v_lshlrev_b32_e32 v192, 4, v6
	v_bitop3_b32 v6, v4, v5, 4 bitop3:0x36
	v_bitop3_b32 v4, v4, v5, 6 bitop3:0x36
	v_lshlrev_b32_e32 v188, 9, v185
	v_lshlrev_b32_e32 v189, 9, v10
	v_lshl_add_u32 v190, v11, 2, s2
	s_cselect_b64 s[2:3], -1, 0
	v_lshlrev_b32_e32 v193, 4, v6
	v_lshlrev_b32_e32 v194, 4, v4
	v_lshlrev_b32_e32 v146, 1, v2
	s_branch .LBB0_2674

; #define SK_WRITE(s_, b) do { LAS unsigned char* bb = lds + (b) * BUF; _Pragma("unroll") for (int i = 0; i < 4; ++i) *(LAS bf16x8*)(bb + st0 + i * 8192) = ra[s_][i]; \
;         _Pragma("unroll") for (int i = 0; i < NW2; ++i) *(LAS bf16x8*)(bb + 32768 + st0 + i * 8192) = rw[s_][i]; } while (0)
; template <class Epi, int NC>
; __device__ __forceinline__ void skinny_phase(const bf16* __restrict__ A, int lda, int a_goff, const bf16* __restrict__ Bt, int ldb, int K, int ncg, int vcu, int G, const Epi& E, LAS float* rs_tab, LAS unsigned char* lds) {
;     ...
;         f32x16 acc[NC] = {};
;         SK_WRITE(0, 0);
;         asm volatile("s_waitcnt lgkmcnt(0)" ::: "memory"); __builtin_amdgcn_s_barrier(); asm volatile("" ::: "memory");
.LBB0_2674:
	v_add_u32_e32 v2, 0, v184
	s_waitcnt vmcnt(8) lgkmcnt(0)
	ds_write_b128 v2, v[36:39]
	ds_write_b128 v2, v[40:43] offset:8192
	ds_write_b128 v2, v[48:51] offset:16384
	ds_write_b128 v2, v[44:47] offset:24576
	ds_write_b128 v2, v[56:59] offset:32768
	ds_write_b128 v2, v[60:63] offset:40960
	ds_write_b128 v2, v[68:71] offset:49152
	ds_write_b128 v2, v[72:75] offset:57344
	s_waitcnt lgkmcnt(0)
	s_barrier
	v_mov_b32_e32 v4, 0
	s_mov_b32 s10, s62
	s_mov_b64 s[12:13], 0
	s_mov_b32 s4, 0
	s_mov_b32 s5, 0
	v_mov_b32_e32 v5, v4
	v_mov_b32_e32 v6, v4
	v_mov_b32_e32 v7, v4
	v_mov_b32_e32 v8, v4
	v_mov_b32_e32 v9, v4
	v_mov_b32_e32 v10, v4
	v_mov_b32_e32 v11, v4
	v_mov_b32_e32 v12, v4
	v_mov_b32_e32 v13, v4
	v_mov_b32_e32 v14, v4
	v_mov_b32_e32 v15, v4
	v_mov_b32_e32 v16, v4
	v_mov_b32_e32 v17, v4
	v_mov_b32_e32 v18, v4
	v_mov_b32_e32 v19, v4
	v_mov_b32_e32 v20, v4
	v_mov_b32_e32 v21, v4
	v_mov_b32_e32 v22, v4
	v_mov_b32_e32 v23, v4
	v_mov_b32_e32 v24, v4
	v_mov_b32_e32 v25, v4
	v_mov_b32_e32 v26, v4
	v_mov_b32_e32 v27, v4
	v_mov_b32_e32 v28, v4
	v_mov_b32_e32 v29, v4
	v_mov_b32_e32 v30, v4
	v_mov_b32_e32 v31, v4
	v_mov_b32_e32 v32, v4
	v_mov_b32_e32 v33, v4
	v_mov_b32_e32 v34, v4
	v_mov_b32_e32 v35, v4
	s_branch .LBB0_2677

.LBB0_2677:
	s_and_b32 s7, s4, 0x10000
	s_xor_b32 s6, s7, 0x10000
	s_add_i32 s6, s6, 0
	s_cmp_lt_u32 s5, 6
	s_cbranch_scc1 .Lsk2674_a
	s_waitcnt vmcnt(0)
.Lsk2674_a:
	s_waitcnt vmcnt(6)
	s_cmp_gt_u32 s5, 4
	s_cselect_b64 s[18:19], -1, 0
	v_add_u32_e32 v2, s6, v184
	s_and_b64 vcc, exec, s[18:19]
	ds_write_b128 v2, v[52:55]
	ds_write_b128 v2, v[64:67] offset:8192
	ds_write_b128 v2, v[80:83] offset:16384
	ds_write_b128 v2, v[76:79] offset:24576
	ds_write_b128 v2, v[88:91] offset:32768
	ds_write_b128 v2, v[92:95] offset:40960
	ds_write_b128 v2, v[100:103] offset:49152
	ds_write_b128 v2, v[104:107] offset:57344
	s_cbranch_vccnz .LBB0_2679
	v_lshl_add_u64 v[44:45], v[142:143], 0, s[12:13]
	v_add_co_u32_e32 v40, vcc, 0x10000, v44
	v_lshl_add_u64 v[56:57], v[134:135], 0, s[12:13]
	s_nop 0
	v_addc_co_u32_e32 v41, vcc, 0, v45, vcc
	v_add_co_u32_e32 v46, vcc, 0x20000, v44
	global_load_dwordx4 v[36:39], v[44:45], off offset:1536
	s_nop 0
	global_load_dwordx4 v[40:43], v[40:41], off offset:1536
	v_addc_co_u32_e32 v47, vcc, 0, v45, vcc
	v_add_co_u32_e32 v44, vcc, 0x30000, v44
	v_lshl_add_u64 v[60:61], v[136:137], 0, s[12:13]
	s_nop 0
	v_addc_co_u32_e32 v45, vcc, 0, v45, vcc
	v_lshl_add_u64 v[68:69], v[138:139], 0, s[12:13]
	v_lshl_add_u64 v[72:73], v[140:141], 0, s[12:13]
	global_load_dwordx4 v[48:51], v[46:47], off offset:1536
	s_nop 0
	global_load_dwordx4 v[44:47], v[44:45], off offset:1536
	s_nop 0
	global_load_dwordx4 v[56:59], v[56:57], off offset:1536
	s_nop 0
	global_load_dwordx4 v[60:63], v[60:61], off offset:1536
	s_nop 0
	global_load_dwordx4 v[68:71], v[68:69], off offset:1536
	s_nop 0
	global_load_dwordx4 v[72:75], v[72:73], off offset:1536
.LBB0_2679:
	s_add_i32 s7, s7, 0
	v_add_u32_e32 v156, s7, v188
	v_add_u32_e32 v157, s7, v189
	v_add_u32_e32 v148, v156, v191
	v_add_u32_e32 v147, v157, v191
	ds_read_b128 v[150:153], v148
	ds_read_b128 v[172:175], v147 offset:32768
	v_add_u32_e32 v149, v156, v192
	s_cmp_lt_u32 s5, 6
	s_cselect_b64 s[20:21], -1, 0
	s_cmp_gt_u32 s5, 5
	s_waitcnt lgkmcnt(0)
	v_mfma_f32_32x32x16_bf16 v[4:19], v[172:175], v[150:153], v[4:19]
	ds_read_b128 v[172:175], v147 offset:49152
	s_waitcnt lgkmcnt(0)
	v_mfma_f32_32x32x16_bf16 v[20:35], v[172:175], v[150:153], v[20:35]
	v_add_u32_e32 v150, v157, v192
	ds_read_b128 v[152:155], v149
	ds_read_b128 v[172:175], v150 offset:32768
	v_add_u32_e32 v151, v157, v193
	ds_read_b128 v[176:179], v151 offset:32768
	s_waitcnt lgkmcnt(0)
	v_mfma_f32_32x32x16_bf16 v[4:19], v[172:175], v[152:155], v[4:19]
	ds_read_b128 v[172:175], v150 offset:49152
	s_waitcnt lgkmcnt(0)
	v_mfma_f32_32x32x16_bf16 v[20:35], v[172:175], v[152:155], v[20:35]
	v_add_u32_e32 v152, v156, v193
	ds_read_b128 v[172:175], v152
	v_add_u32_e32 v154, v156, v194
	v_add_u32_e32 v153, v157, v194
	s_waitcnt lgkmcnt(0)
	v_mfma_f32_32x32x16_bf16 v[4:19], v[176:179], v[172:175], v[4:19]
	ds_read_b128 v[176:179], v151 offset:49152
	s_waitcnt lgkmcnt(0)
	v_mfma_f32_32x32x16_bf16 v[20:35], v[176:179], v[172:175], v[20:35]
	ds_read_b128 v[172:175], v154
	ds_read_b128 v[176:179], v153 offset:32768
	s_waitcnt lgkmcnt(0)
	v_mfma_f32_32x32x16_bf16 v[4:19], v[176:179], v[172:175], v[4:19]
	ds_read_b128 v[176:179], v153 offset:49152
	s_waitcnt lgkmcnt(0)
	s_barrier
	s_waitcnt lgkmcnt(0)
	v_mfma_f32_32x32x16_bf16 v[20:35], v[176:179], v[172:175], v[20:35]
	s_cbranch_scc1 .LBB0_2681
	v_add_u32_e32 v155, s7, v184
	s_waitcnt vmcnt(8)
	ds_write_b128 v155, v[84:87]
	ds_write_b128 v155, v[96:99] offset:8192
	ds_write_b128 v155, v[108:111] offset:16384
	ds_write_b128 v155, v[112:115] offset:24576
	ds_write_b128 v155, v[116:119] offset:32768
	ds_write_b128 v155, v[120:123] offset:40960
	ds_write_b128 v155, v[124:127] offset:49152
	ds_write_b128 v155, v[128:131] offset:57344
.LBB0_2681:
	s_cmp_gt_u32 s5, 3
	s_cbranch_scc1 .LBB0_2683
	v_lshl_add_u64 v[76:77], v[142:143], 0, s[12:13]
	v_add_co_u32_e32 v64, vcc, 0x10000, v76
	v_lshl_add_u64 v[88:89], v[134:135], 0, s[12:13]
	s_nop 0
	v_addc_co_u32_e32 v65, vcc, 0, v77, vcc
	v_add_co_u32_e32 v78, vcc, 0x20000, v76
	global_load_dwordx4 v[52:55], v[76:77], off offset:2048
	s_nop 0
	global_load_dwordx4 v[64:67], v[64:65], off offset:2048
	v_addc_co_u32_e32 v79, vcc, 0, v77, vcc
	v_add_co_u32_e32 v76, vcc, 0x30000, v76
	v_lshl_add_u64 v[92:93], v[136:137], 0, s[12:13]
	s_nop 0
	v_addc_co_u32_e32 v77, vcc, 0, v77, vcc
	v_lshl_add_u64 v[100:101], v[138:139], 0, s[12:13]
	v_lshl_add_u64 v[104:105], v[140:141], 0, s[12:13]
	global_load_dwordx4 v[80:83], v[78:79], off offset:2048
	s_nop 0
	global_load_dwordx4 v[76:79], v[76:77], off offset:2048
	s_nop 0
	global_load_dwordx4 v[88:91], v[88:89], off offset:2048
	s_nop 0
	global_load_dwordx4 v[92:95], v[92:93], off offset:2048
	s_nop 0
	global_load_dwordx4 v[100:103], v[100:101], off offset:2048
	s_nop 0
	global_load_dwordx4 v[104:107], v[104:105], off offset:2048
; #define SK_LOAD3() do { SK_LOAD(0, 0); if (1 < nsc) SK_LOAD(1, 1); if (2 < nsc) SK_LOAD(2, 2); } while (0)
; template <class Epi, int NC>
; __device__ __forceinline__ void skinny_phase(const bf16* __restrict__ A, int lda, int a_goff, const bf16* __restrict__ Bt, int ldb, int K, int ncg, int vcu, int G, const Epi& E, LAS float* rs_tab, LAS unsigned char* lds) {
;     ...
;         const int un = u + G;
;         if (un < NU) { SK_PTRS(un); SK_LOAD3(); }
.LBB0_2683:
	v_add_u32_e32 v155, s6, v188
	v_add_u32_e32 v156, s6, v189
	v_add_u32_e32 v157, v155, v191
	ds_read_b128 v[172:175], v157
	v_add_u32_e32 v157, v156, v191
	ds_read_b128 v[176:179], v157 offset:32768
	s_andn2_b64 vcc, exec, s[20:21]
	s_waitcnt lgkmcnt(0)
	v_mfma_f32_32x32x16_bf16 v[4:19], v[176:179], v[172:175], v[4:19]
	ds_read_b128 v[176:179], v157 offset:49152
	v_add_u32_e32 v157, v155, v192
	s_waitcnt lgkmcnt(0)
	v_mfma_f32_32x32x16_bf16 v[20:35], v[176:179], v[172:175], v[20:35]
	ds_read_b128 v[172:175], v157
	v_add_u32_e32 v157, v156, v192
	ds_read_b128 v[176:179], v157 offset:32768
	s_waitcnt lgkmcnt(0)
	v_mfma_f32_32x32x16_bf16 v[4:19], v[176:179], v[172:175], v[4:19]
	ds_read_b128 v[176:179], v157 offset:49152
	v_add_u32_e32 v157, v155, v193
	v_add_u32_e32 v155, v155, v194
	s_waitcnt lgkmcnt(0)
	v_mfma_f32_32x32x16_bf16 v[20:35], v[176:179], v[172:175], v[20:35]
	ds_read_b128 v[172:175], v157
	v_add_u32_e32 v157, v156, v193
	ds_read_b128 v[176:179], v157 offset:32768
	s_waitcnt lgkmcnt(0)
	v_mfma_f32_32x32x16_bf16 v[4:19], v[176:179], v[172:175], v[4:19]
	ds_read_b128 v[176:179], v157 offset:49152
	s_waitcnt lgkmcnt(0)
	v_mfma_f32_32x32x16_bf16 v[20:35], v[176:179], v[172:175], v[20:35]
	ds_read_b128 v[172:175], v155
	v_add_u32_e32 v155, v156, v194
	ds_read_b128 v[176:179], v155 offset:32768
	s_waitcnt lgkmcnt(0)
	v_mfma_f32_32x32x16_bf16 v[4:19], v[176:179], v[172:175], v[4:19]
	ds_read_b128 v[176:179], v155 offset:49152
	s_waitcnt lgkmcnt(0)
	s_barrier
	s_waitcnt lgkmcnt(0)
	v_mfma_f32_32x32x16_bf16 v[20:35], v[176:179], v[172:175], v[20:35]
	s_cbranch_vccnz .LBB0_2676
	s_cmpk_eq_i32 s12, 0xa00
	s_cbranch_scc1 .LBB0_2686
	s_waitcnt vmcnt(8)
	ds_write_b128 v2, v[36:39]
	ds_write_b128 v2, v[40:43] offset:8192
	ds_write_b128 v2, v[48:51] offset:16384
	ds_write_b128 v2, v[44:47] offset:24576
	ds_write_b128 v2, v[56:59] offset:32768
	ds_write_b128 v2, v[60:63] offset:40960
	ds_write_b128 v2, v[68:71] offset:49152
	ds_write_b128 v2, v[72:75] offset:57344
.LBB0_2686:
	s_cmp_gt_u32 s5, 2
	s_cbranch_scc1 .LBB0_2675
	v_lshl_add_u64 v[108:109], v[142:143], 0, s[12:13]
	v_add_co_u32_e32 v96, vcc, 0x10000, v108
	v_lshl_add_u64 v[116:117], v[134:135], 0, s[12:13]
	s_nop 0
	v_addc_co_u32_e32 v97, vcc, 0, v109, vcc
	v_add_co_u32_e32 v110, vcc, 0x20000, v108
	v_lshl_add_u64 v[120:121], v[136:137], 0, s[12:13]
	s_nop 0
	v_addc_co_u32_e32 v111, vcc, 0, v109, vcc
	v_add_co_u32_e32 v112, vcc, 0x30000, v108
	v_lshl_add_u64 v[124:125], v[138:139], 0, s[12:13]
	s_nop 0
	v_addc_co_u32_e32 v113, vcc, 0, v109, vcc
	v_lshl_add_u64 v[128:129], v[140:141], 0, s[12:13]
	global_load_dwordx4 v[84:87], v[108:109], off offset:2560
	s_nop 0
	global_load_dwordx4 v[96:99], v[96:97], off offset:2560
	s_nop 0
	global_load_dwordx4 v[108:111], v[110:111], off offset:2560
	s_nop 0
	global_load_dwordx4 v[112:115], v[112:113], off offset:2560
	s_nop 0
	global_load_dwordx4 v[116:119], v[116:117], off offset:2560
	s_nop 0
	global_load_dwordx4 v[120:123], v[120:121], off offset:2560
	s_nop 0
	global_load_dwordx4 v[124:127], v[124:125], off offset:2560
	s_nop 0
	global_load_dwordx4 v[128:131], v[128:129], off offset:2560
	s_branch .LBB0_2675
.LBB0_2688:
	s_add_i32 s62, s10, s59
	s_cmpk_gt_i32 s62, 0x2bf
	s_cselect_b64 s[12:13], -1, 0
	s_cmpk_lt_i32 s62, 0x2c0
	s_cbranch_scc0 .LBB0_2690
	s_lshl_b32 s5, s62, 6
	s_ashr_i32 s4, s62, 1
	s_and_b32 s5, s5, 0xc0
	s_waitcnt vmcnt(0)
	v_add_u32_e32 v36, s5, v182
	s_lshl_b32 s5, s4, 5
	s_lshl_b32 s4, s4, 4
	s_and_b32 s5, s5, 0xffffff00
	s_and_b32 s4, s4, 0x60
	s_or_b32 s4, s4, s5
	v_or_b32_e32 v2, s4, v183
	v_add_u32_e32 v38, v2, v186
	v_ashrrev_i32_e32 v39, 31, v38
	v_lshlrev_b64 v[38:39], 12, v[38:39]
	v_lshl_add_u64 v[134:135], v[132:133], 0, v[38:39]
	v_add_u32_e32 v38, v2, v187
	v_ashrrev_i32_e32 v37, 31, v36
	v_ashrrev_i32_e32 v39, 31, v38
	v_lshlrev_b64 v[36:37], 12, v[36:37]
	v_lshlrev_b64 v[38:39], 12, v[38:39]
	v_or_b32_e32 v2, 16, v2
	v_lshl_add_u64 v[136:137], v[132:133], 0, v[38:39]
	v_add_u32_e32 v38, v2, v186
	v_lshl_add_u64 v[142:143], v[144:145], 0, v[36:37]
	v_ashrrev_i32_e32 v39, 31, v38
	v_lshlrev_b64 v[38:39], 12, v[38:39]
	v_add_co_u32_e32 v80, vcc, s71, v142
	v_lshl_add_u64 v[138:139], v[132:133], 0, v[38:39]
	s_nop 0
	v_addc_co_u32_e32 v81, vcc, 0, v143, vcc
	v_add_u32_e32 v38, v2, v187
	v_add_co_u32_e32 v108, vcc, s81, v142
	v_ashrrev_i32_e32 v39, 31, v38
	s_nop 0
	v_addc_co_u32_e32 v109, vcc, 0, v143, vcc
	s_mov_b32 s4, 0x30000
	v_lshlrev_b64 v[38:39], 12, v[38:39]
	v_add_co_u32_e32 v112, vcc, s4, v142
	v_lshl_add_u64 v[140:141], v[132:133], 0, v[38:39]
	s_nop 0
	v_addc_co_u32_e32 v113, vcc, 0, v143, vcc
	global_load_dwordx4 v[36:39], v[142:143], off
	global_load_dwordx4 v[52:55], v[142:143], off offset:512
	global_load_dwordx4 v[40:43], v[80:81], off
	global_load_dwordx4 v[64:67], v[80:81], off offset:512
	global_load_dwordx4 v[44:47], v[112:113], off
	global_load_dwordx4 v[76:79], v[112:113], off offset:512
	global_load_dwordx4 v[56:59], v[134:135], off
	global_load_dwordx4 v[88:91], v[134:135], off offset:512
	global_load_dwordx4 v[60:63], v[136:137], off
	global_load_dwordx4 v[92:95], v[136:137], off offset:512
	global_load_dwordx4 v[68:71], v[138:139], off
	global_load_dwordx4 v[100:103], v[138:139], off offset:512
	global_load_dwordx4 v[72:75], v[140:141], off
	global_load_dwordx4 v[104:107], v[140:141], off offset:512
	global_load_dwordx4 v[84:87], v[142:143], off offset:1024
	global_load_dwordx4 v[48:51], v[108:109], off
	global_load_dwordx4 v[96:99], v[80:81], off offset:1024
	s_nop 0
	global_load_dwordx4 v[80:83], v[108:109], off offset:512
	s_nop 0
	global_load_dwordx4 v[108:111], v[108:109], off offset:1024
	s_nop 0
	global_load_dwordx4 v[112:115], v[112:113], off offset:1024
	s_nop 0
	global_load_dwordx4 v[116:119], v[134:135], off offset:1024
	global_load_dwordx4 v[120:123], v[136:137], off offset:1024
	global_load_dwordx4 v[124:127], v[138:139], off offset:1024
	global_load_dwordx4 v[128:131], v[140:141], off offset:1024

; __device__ __forceinline__ int opaque_tid() { int t = threadIdx.x; asm volatile("" : "+v"(t)); return t; }
; #define SK_LOAD3() do { SK_LOAD(0, 0); if (1 < nsc) SK_LOAD(1, 1); if (2 < nsc) SK_LOAD(2, 2); } while (0)
; template <class Epi, int NC>
; __device__ __forceinline__ void skinny_phase(const bf16* __restrict__ A, int lda, int a_goff, const bf16* __restrict__ Bt, int ldb, int K, int ncg, int vcu, int G, const Epi& E, LAS float* rs_tab, LAS unsigned char* lds) {
;     const int tid = opaque_tid(), w = __builtin_amdgcn_readfirstlane(tid >> 6), lane = tid & 63, r32 = lane & 31, hi = lane >> 5, rblk = w & 1, kq = w >> 1;
;     if (Epi::NEEDS_RS) { if (tid < 256) rs_tab[tid] = row_scale_s(E.ssqS, tid); }
;     asm volatile("s_waitcnt lgkmcnt(0)" ::: "memory"); __builtin_amdgcn_s_barrier(); asm volatile("" ::: "memory");
;     constexpr int BUF = 32768 + NC * 16384, NW2 = 2 * NC;
;     const int srow = tid >> 5, sslot = tid & 31, nsc = K / 256;
;     const int st0 = srow * 512 + ((sslot ^ (srow & 15)) << 4);
;     const int rrow = 32 * rblk + r32;
;     const int NU = 4 * (ncg / NC);
;     bf16x8 ra[3][4], rw[3][NW2];
;     const bf16* pa = A; const bf16* pw[NW2];
; #pragma unroll
;     for (int i = 0; i < NW2; ++i) pw[i] = Bt;
;     ...
;     int u = vcu;
;     if (u < NU) { SK_PTRS(u); SK_LOAD3(); }
.LBB0_2795:
	s_add_u32 s18, s2, 0x2f400000
	s_waitcnt vmcnt(0)
	v_mov_b32_e32 v4, v0
	s_addc_u32 s19, s3, 0
	s_waitcnt lgkmcnt(0)
	s_barrier
	s_waitcnt lgkmcnt(0)
	v_and_b32_e32 v5, 31, v4
	s_cmpk_lt_i32 s62, 0x100
	v_readfirstlane_b32 s4, v4
	v_ashrrev_i32_e32 v104, 5, v4
	s_cselect_b64 s[20:21], -1, 0
	s_cmpk_gt_i32 s62, 0xff
	v_mov_b64_e32 v[92:93], s[12:13]
	v_mov_b64_e32 v[94:95], s[18:19]
	v_lshlrev_b32_e32 v2, 4, v5
	v_mov_b64_e32 v[96:97], s[12:13]
	s_cbranch_scc1 .LBB0_2797
	s_lshl_b32 s5, s62, 6
	s_and_b32 s5, s5, 0xc0
	v_add_u32_e32 v8, s5, v104
	s_lshl_b32 s5, s62, 3
	s_andn2_b32 s5, s5, 31
	v_add_u32_e32 v9, s5, v104
	v_lshl_add_u64 v[6:7], s[12:13], 0, v[2:3]
	s_movk_i32 s5, 0x2c00
	v_mad_i64_i32 v[96:97], s[6:7], v9, s5, v[6:7]
	v_add_u32_e32 v9, 16, v9
	v_mad_i64_i32 v[92:93], s[6:7], v9, s5, v[6:7]
	v_mov_b64_e32 v[6:7], s[18:19]
	v_mad_i64_i32 v[6:7], s[6:7], v8, s5, v[6:7]
	v_lshl_add_u64 v[94:95], v[6:7], 0, v[2:3]
	s_mov_b32 s5, 0x2c000
	s_nop 0
	v_add_co_u32_e32 v6, vcc, s5, v94
	s_mov_b32 s5, 0x58000
	s_nop 0
	v_addc_co_u32_e32 v7, vcc, 0, v95, vcc
	v_add_co_u32_e32 v8, vcc, s5, v94
	s_mov_b32 s5, 0x84000
	s_nop 0
	v_addc_co_u32_e32 v9, vcc, 0, v95, vcc
	v_add_co_u32_e32 v10, vcc, s5, v94
	s_nop 1
	v_addc_co_u32_e32 v11, vcc, 0, v95, vcc
	global_load_dwordx4 v[20:23], v[94:95], off
	global_load_dwordx4 v[24:27], v[94:95], off offset:512
	global_load_dwordx4 v[32:35], v[6:7], off
	global_load_dwordx4 v[28:31], v[6:7], off offset:512
	global_load_dwordx4 v[48:51], v[10:11], off
	global_load_dwordx4 v[44:47], v[10:11], off offset:512
	global_load_dwordx4 v[72:75], v[96:97], off
	global_load_dwordx4 v[68:71], v[96:97], off offset:512
	global_load_dwordx4 v[80:83], v[92:93], off
	global_load_dwordx4 v[76:79], v[92:93], off offset:512
	global_load_dwordx4 v[36:39], v[94:95], off offset:1024
	global_load_dwordx4 v[60:63], v[8:9], off
	global_load_dwordx4 v[40:43], v[6:7], off offset:1024
	global_load_dwordx4 v[56:59], v[8:9], off offset:512
	global_load_dwordx4 v[52:55], v[8:9], off offset:1024
	global_load_dwordx4 v[64:67], v[10:11], off offset:1024
	global_load_dwordx4 v[84:87], v[96:97], off offset:1024
	global_load_dwordx4 v[88:91], v[92:93], off offset:1024

.LBB0_2804:
	s_cmp_lt_u32 s5, 19
	s_cselect_b64 s[40:41], -1, 0
	s_cmp_gt_u32 s5, 18
	s_cselect_b64 s[36:37], -1, 0
	s_and_b64 vcc, exec, s[36:37]
	s_cbranch_vccnz .LBB0_2806
	s_waitcnt vmcnt(0)
	v_lshl_add_u64 v[48:49], v[94:95], 0, s[20:21]
	v_add_co_u32_e32 v32, vcc, 0x2c000, v48
	v_lshl_add_u64 v[72:73], v[96:97], 0, s[20:21]
	s_nop 0
	v_addc_co_u32_e32 v33, vcc, 0, v49, vcc
	v_add_co_u32_e32 v50, vcc, 0x58000, v48
	global_load_dwordx4 v[20:23], v[48:49], off offset:1536
	s_nop 0
	global_load_dwordx4 v[32:35], v[32:33], off offset:1536
	v_addc_co_u32_e32 v51, vcc, 0, v49, vcc
	v_add_co_u32_e32 v48, vcc, 0x84000, v48
	v_lshl_add_u64 v[80:81], v[92:93], 0, s[20:21]
	s_nop 0
	v_addc_co_u32_e32 v49, vcc, 0, v49, vcc
	global_load_dwordx4 v[60:63], v[50:51], off offset:1536
	s_nop 0
	global_load_dwordx4 v[48:51], v[48:49], off offset:1536
	s_nop 0
	global_load_dwordx4 v[72:75], v[72:73], off offset:1536
	s_nop 0
	global_load_dwordx4 v[80:83], v[80:81], off offset:1536

.LBB0_2809:
	s_cmp_gt_u32 s5, 17
	s_cbranch_scc1 .LBB0_2811
	s_waitcnt vmcnt(0)
	v_lshl_add_u64 v[44:45], v[94:95], 0, s[20:21]
	v_add_co_u32_e32 v28, vcc, 0x2c000, v44
	v_lshl_add_u64 v[68:69], v[96:97], 0, s[20:21]
	s_nop 0
	v_addc_co_u32_e32 v29, vcc, 0, v45, vcc
	v_add_co_u32_e32 v46, vcc, 0x58000, v44
	global_load_dwordx4 v[24:27], v[44:45], off offset:2048
	s_nop 0
	global_load_dwordx4 v[28:31], v[28:29], off offset:2048
	v_addc_co_u32_e32 v47, vcc, 0, v45, vcc
	v_add_co_u32_e32 v44, vcc, 0x84000, v44
	v_lshl_add_u64 v[76:77], v[92:93], 0, s[20:21]
	s_nop 0
	v_addc_co_u32_e32 v45, vcc, 0, v45, vcc
	global_load_dwordx4 v[56:59], v[46:47], off offset:2048
	s_nop 0
	global_load_dwordx4 v[44:47], v[44:45], off offset:2048
	s_nop 0
	global_load_dwordx4 v[68:71], v[68:69], off offset:2048
	s_nop 0
	global_load_dwordx4 v[76:79], v[76:77], off offset:2048

.LBB0_2816:
	s_cmp_gt_u32 s5, 16
	s_cbranch_scc1 .LBB0_2818
	s_waitcnt vmcnt(0)
	v_lshl_add_u64 v[52:53], v[94:95], 0, s[20:21]
	v_add_co_u32_e32 v40, vcc, 0x2c000, v52
	v_lshl_add_u64 v[84:85], v[96:97], 0, s[20:21]
	s_nop 0
	v_addc_co_u32_e32 v41, vcc, 0, v53, vcc
	v_add_co_u32_e32 v54, vcc, 0x58000, v52
	v_lshl_add_u64 v[88:89], v[92:93], 0, s[20:21]
	s_nop 0
	v_addc_co_u32_e32 v55, vcc, 0, v53, vcc
	v_add_co_u32_e32 v64, vcc, 0x84000, v52
	global_load_dwordx4 v[36:39], v[52:53], off offset:2560
	s_nop 0
	global_load_dwordx4 v[40:43], v[40:41], off offset:2560
	v_addc_co_u32_e32 v65, vcc, 0, v53, vcc
	global_load_dwordx4 v[52:55], v[54:55], off offset:2560
	s_nop 0
	global_load_dwordx4 v[64:67], v[64:65], off offset:2560
	s_nop 0
	global_load_dwordx4 v[84:87], v[84:85], off offset:2560
	s_nop 0
	global_load_dwordx4 v[88:91], v[88:89], off offset:2560

; #define SK_LOAD3() do { SK_LOAD(0, 0); if (1 < nsc) SK_LOAD(1, 1); if (2 < nsc) SK_LOAD(2, 2); } while (0)
; template <class Epi, int NC>
; __device__ __forceinline__ void skinny_phase(const bf16* __restrict__ A, int lda, int a_goff, const bf16* __restrict__ Bt, int ldb, int K, int ncg, int vcu, int G, const Epi& E, LAS float* rs_tab, LAS unsigned char* lds) {
;     ...
;         const int un = u + G;
;         if (un < NU) { SK_PTRS(un); SK_LOAD3(); }
.LBB0_2820:
	s_add_i32 s62, s4, s59
	s_cmpk_gt_i32 s62, 0xff
	s_cselect_b64 s[20:21], -1, 0
	s_cmpk_lt_i32 s62, 0x100
	s_cbranch_scc0 .LBB0_2822
	s_lshl_b32 s5, s62, 6
	s_and_b32 s5, s5, 0xc0
	v_add_u32_e32 v2, s5, v104
	s_waitcnt vmcnt(0)
	v_mov_b64_e32 v[20:21], s[18:19]
	s_movk_i32 s9, 0x2c00
	v_mad_i64_i32 v[20:21], s[6:7], v2, s9, v[20:21]
	v_mov_b32_e32 v101, v3
	s_lshl_b32 s5, s62, 3
	v_lshl_add_u64 v[94:95], v[20:21], 0, v[100:101]
	s_andn2_b32 s5, s5, 31
	v_add_u32_e32 v2, s5, v104
	v_add_co_u32_e32 v40, vcc, s10, v94
	s_mov_b32 s5, 0x58000
	s_nop 0
	v_addc_co_u32_e32 v41, vcc, 0, v95, vcc
	v_add_co_u32_e32 v52, vcc, s5, v94
	s_mov_b32 s5, 0x84000
	s_nop 0
	v_addc_co_u32_e32 v53, vcc, 0, v95, vcc
	v_mad_i64_i32 v[96:97], s[6:7], v2, s9, v[98:99]
	v_add_u32_e32 v2, 16, v2
	v_add_co_u32_e32 v64, vcc, s5, v94
	v_mad_i64_i32 v[92:93], s[6:7], v2, s9, v[98:99]
	s_nop 0
	v_addc_co_u32_e32 v65, vcc, 0, v95, vcc
	global_load_dwordx4 v[20:23], v[94:95], off
	global_load_dwordx4 v[24:27], v[94:95], off offset:512
	global_load_dwordx4 v[32:35], v[40:41], off
	global_load_dwordx4 v[28:31], v[40:41], off offset:512
	global_load_dwordx4 v[48:51], v[64:65], off
	global_load_dwordx4 v[44:47], v[64:65], off offset:512
	global_load_dwordx4 v[72:75], v[96:97], off
	global_load_dwordx4 v[68:71], v[96:97], off offset:512
	global_load_dwordx4 v[80:83], v[92:93], off
	global_load_dwordx4 v[76:79], v[92:93], off offset:512
	global_load_dwordx4 v[36:39], v[94:95], off offset:1024
	global_load_dwordx4 v[60:63], v[52:53], off
	s_nop 0
	global_load_dwordx4 v[40:43], v[40:41], off offset:1024
	s_nop 0
	global_load_dwordx4 v[56:59], v[52:53], off offset:512
	s_nop 0
	global_load_dwordx4 v[52:55], v[52:53], off offset:1024
	s_nop 0
	global_load_dwordx4 v[64:67], v[64:65], off offset:1024
	s_nop 0
	global_load_dwordx4 v[84:87], v[96:97], off offset:1024
	global_load_dwordx4 v[88:91], v[92:93], off offset:1024
